# K-loops: per-segment s_setprio 1/0 toggling around the MFMA blocks removed (all six loops)
# speedup vs baseline: 1.0049x; 1.0049x over previous
; #define G_STAGE(bufoff, gbase, voff) do { _Pragma("unroll") for (int _i = 0; _i < 2; ++_i) \
;         __builtin_amdgcn_global_load_lds((const unsigned*)((const char*)(gbase) + (voff)[_i]), (LAS unsigned*)(lds + (bufoff) + ldsw + _i * 8192), 16, 0, 0); } while (0)
; #define G_WAIT_V(n) asm volatile("s_waitcnt vmcnt(" #n ")" ::: "memory")
; #define G_WAIT_L(n) asm volatile("s_waitcnt lgkmcnt(" #n ")" ::: "memory")
; #define G_BAR __builtin_amdgcn_s_barrier()
; #define G_SCHED __builtin_amdgcn_sched_barrier(0)
; template <int MODE  , class Epi, class Sched>
; __device__ __forceinline__ void gemm_phase(LAS unsigned char* lds, const GemmDesc g, const Sched& S, const Epi& E) {
;     ...
;             G_LDB(B0, 0, 0); G_SCHED; G_LDA(At, 0, 0); G_STAGE(G_SA(1, 1), a1 + hstepA, voffA);
;             G_WAIT_L(8); G_BAR; G_WAIT_L(0); G_MMA(0, 0, At, B0); G_BAR; G_SCHED;
;             G_LDB(B1, 0, 1); G_STAGE(G_SB(0, 0), b2, voffB);
;             G_BAR; G_WAIT_L(0); G_MMA(0, 1, At, B1); G_BAR;
;             G_LDA(At, 0, 1); G_STAGE(G_SA(0, 0), a2, voffA);
;             G_BAR; G_WAIT_L(0); G_MMA(1, 0, At, B0); G_BAR; G_SCHED;
;             G_STAGE(G_SB(0, 1), b2 + hstepB, voffB);
;             G_WAIT_V(6); G_BAR; G_MMA(1, 1, At, B1); G_BAR;
.Lnodb_p1c:
.LBB0_527:
	s_add_u32 s40, s34, 0x100
	s_addc_u32 s41, s35, 0
	s_cmp_eq_u32 s77, 12
	s_cselect_b32 s47, s21, s41
	s_cselect_b32 s46, s20, s40
	s_cselect_b32 s45, s3, s76
	s_cselect_b32 s44, s2, s72
	s_mov_b32 m0, s64
	s_add_u32 s98, s34, 0x44080
	s_addc_u32 s99, s35, 0
	ds_read_b128 v[162:165], v194
	ds_read_b128 v[166:169], v194 offset:1024
	ds_read_b128 v[170:173], v194 offset:2048
	ds_read_b128 v[174:177], v194 offset:3072
	ds_read_b128 v[178:181], v194 offset:4096
	ds_read_b128 v[182:185], v194 offset:5120
	ds_read_b128 v[186:189], v194 offset:6144
	ds_read_b128 v[198:201], v194 offset:7168
	global_load_lds_dwordx4 v146, s[98:99]
	s_mov_b32 m0, s65
	s_nop 0
	global_load_lds_dwordx4 v150, s[98:99]
	s_waitcnt lgkmcnt(8)
	s_barrier
	s_waitcnt lgkmcnt(0)
	s_waitcnt lgkmcnt(0)
	v_mfma_i32_16x16x64_i8 v[134:137], v[232:235], v[162:165], v[134:137]
	v_mfma_i32_16x16x64_i8 v[130:133], v[240:243], v[162:165], v[130:133]
	v_mfma_i32_16x16x64_i8 v[118:121], v[232:235], v[170:173], v[118:121]
	v_mfma_i32_16x16x64_i8 v[114:117], v[240:243], v[170:173], v[114:117]
	v_mfma_i32_16x16x64_i8 v[102:105], v[232:235], v[178:181], v[102:105]
	v_mfma_i32_16x16x64_i8 v[98:101], v[240:243], v[178:181], v[98:101]
	v_mfma_i32_16x16x64_i8 v[86:89], v[232:235], v[186:189], v[86:89]
	v_mfma_i32_16x16x64_i8 v[82:85], v[240:243], v[186:189], v[82:85]
	v_mfma_i32_16x16x64_i8 v[134:137], v[236:239], v[166:169], v[134:137]
	v_mfma_i32_16x16x64_i8 v[130:133], v[244:247], v[166:169], v[130:133]
	v_mfma_i32_16x16x64_i8 v[118:121], v[236:239], v[174:177], v[118:121]
	v_mfma_i32_16x16x64_i8 v[114:117], v[244:247], v[174:177], v[114:117]
	v_mfma_i32_16x16x64_i8 v[102:105], v[236:239], v[182:185], v[102:105]
	v_mfma_i32_16x16x64_i8 v[98:101], v[244:247], v[182:185], v[98:101]
	v_mfma_i32_16x16x64_i8 v[86:89], v[236:239], v[198:201], v[86:89]
	v_mfma_i32_16x16x64_i8 v[82:85], v[244:247], v[198:201], v[82:85]
	s_barrier
	s_mov_b32 m0, s66
	ds_read_b128 v[202:205], v195
	ds_read_b128 v[206:209], v195 offset:1024
	ds_read_b128 v[210:213], v195 offset:2048
	ds_read_b128 v[214:217], v195 offset:3072
	global_load_lds_dwordx4 v148, s[44:45]
	s_mov_b32 m0, s67
	s_nop 0
	global_load_lds_dwordx4 v152, s[44:45]
	s_barrier
	s_waitcnt lgkmcnt(0)
	s_waitcnt lgkmcnt(0)
	v_mfma_i32_16x16x64_i8 v[142:145], v[202:205], v[162:165], v[142:145]
	v_mfma_i32_16x16x64_i8 v[138:141], v[210:213], v[162:165], v[138:141]
	v_mfma_i32_16x16x64_i8 v[126:129], v[202:205], v[170:173], v[126:129]
	v_mfma_i32_16x16x64_i8 v[122:125], v[210:213], v[170:173], v[122:125]
	v_mfma_i32_16x16x64_i8 v[110:113], v[202:205], v[178:181], v[110:113]
	v_mfma_i32_16x16x64_i8 v[106:109], v[210:213], v[178:181], v[106:109]
	v_mfma_i32_16x16x64_i8 v[94:97], v[202:205], v[186:189], v[94:97]
	v_mfma_i32_16x16x64_i8 v[90:93], v[210:213], v[186:189], v[90:93]
	v_mfma_i32_16x16x64_i8 v[142:145], v[206:209], v[166:169], v[142:145]
	v_mfma_i32_16x16x64_i8 v[138:141], v[214:217], v[166:169], v[138:141]
	v_mfma_i32_16x16x64_i8 v[126:129], v[206:209], v[174:177], v[126:129]
	v_mfma_i32_16x16x64_i8 v[122:125], v[214:217], v[174:177], v[122:125]
	v_mfma_i32_16x16x64_i8 v[110:113], v[206:209], v[182:185], v[110:113]
	v_mfma_i32_16x16x64_i8 v[106:109], v[214:217], v[182:185], v[106:109]
	v_mfma_i32_16x16x64_i8 v[94:97], v[206:209], v[198:201], v[94:97]
	v_mfma_i32_16x16x64_i8 v[90:93], v[214:217], v[198:201], v[90:93]
	s_mov_b32 m0, s55
	s_barrier
	ds_read_b128 v[162:165], v194 offset:16384
	ds_read_b128 v[166:169], v194 offset:17408
	ds_read_b128 v[170:173], v194 offset:18432
	ds_read_b128 v[174:177], v194 offset:19456
	ds_read_b128 v[178:181], v194 offset:20480
	ds_read_b128 v[182:185], v194 offset:21504
	ds_read_b128 v[186:189], v194 offset:22528
	ds_read_b128 v[198:201], v194 offset:23552
	global_load_lds_dwordx4 v146, s[46:47]
	s_mov_b32 m0, s56
	s_nop 0
	global_load_lds_dwordx4 v150, s[46:47]
	s_barrier
	s_waitcnt lgkmcnt(0)
	s_waitcnt lgkmcnt(0)
	v_mfma_i32_16x16x64_i8 v[70:73], v[232:235], v[162:165], v[70:73]
	v_mfma_i32_16x16x64_i8 v[66:69], v[240:243], v[162:165], v[66:69]
	v_mfma_i32_16x16x64_i8 v[54:57], v[232:235], v[170:173], v[54:57]
	v_mfma_i32_16x16x64_i8 v[50:53], v[240:243], v[170:173], v[50:53]
	v_mfma_i32_16x16x64_i8 v[22:25], v[232:235], v[178:181], v[22:25]
	v_mfma_i32_16x16x64_i8 v[18:21], v[240:243], v[178:181], v[18:21]
	v_mfma_i32_16x16x64_i8 v[6:9], v[232:235], v[186:189], v[6:9]
	v_mfma_i32_16x16x64_i8 v[2:5], v[240:243], v[186:189], v[2:5]
	v_mfma_i32_16x16x64_i8 v[70:73], v[236:239], v[166:169], v[70:73]
	v_mfma_i32_16x16x64_i8 v[66:69], v[244:247], v[166:169], v[66:69]
	v_mfma_i32_16x16x64_i8 v[54:57], v[236:239], v[174:177], v[54:57]
	v_mfma_i32_16x16x64_i8 v[50:53], v[244:247], v[174:177], v[50:53]
	v_mfma_i32_16x16x64_i8 v[22:25], v[236:239], v[182:185], v[22:25]
	v_mfma_i32_16x16x64_i8 v[18:21], v[244:247], v[182:185], v[18:21]
	v_mfma_i32_16x16x64_i8 v[6:9], v[236:239], v[198:201], v[6:9]
	v_mfma_i32_16x16x64_i8 v[2:5], v[244:247], v[198:201], v[2:5]
	s_barrier
	s_mov_b32 m0, s68
	s_add_u32 s0, s44, 0x44000
	s_addc_u32 s1, s45, 0
	global_load_lds_dwordx4 v148, s[0:1]
	s_mov_b32 m0, s69
	s_nop 0
	global_load_lds_dwordx4 v152, s[0:1]
	s_waitcnt vmcnt(6)
	s_barrier
; #define G_STAGE(bufoff, gbase, voff) do { _Pragma("unroll") for (int _i = 0; _i < 2; ++_i) \
;         __builtin_amdgcn_global_load_lds((const unsigned*)((const char*)(gbase) + (voff)[_i]), (LAS unsigned*)(lds + (bufoff) + ldsw + _i * 8192), 16, 0, 0); } while (0)
; #define G_WAIT_V(n) asm volatile("s_waitcnt vmcnt(" #n ")" ::: "memory")
; #define G_WAIT_L(n) asm volatile("s_waitcnt lgkmcnt(" #n ")" ::: "memory")
; #define G_BAR __builtin_amdgcn_s_barrier()
; #define G_SCHED __builtin_amdgcn_sched_barrier(0)
; template <int MODE  , class Epi, class Sched>
; __device__ __forceinline__ void gemm_phase(LAS unsigned char* lds, const GemmDesc g, const Sched& S, const Epi& E) {
;     ...
;             G_WAIT_V(6); G_BAR; G_MMA(1, 1, At, B1); G_BAR;
;             G_LDB(B0, 1, 0); G_SCHED; G_LDA(At, 1, 0); G_STAGE(G_SA(0, 1), a2 + hstepA, voffA);
;             G_WAIT_L(8); G_BAR; G_WAIT_L(0); G_MMA(0, 0, At, B0); G_BAR; G_SCHED;
;             G_LDB(B1, 1, 1); G_STAGE(G_SB(1, 0), b3, voffB);
	v_mfma_i32_16x16x64_i8 v[30:33], v[202:205], v[178:181], v[30:33]
	v_mfma_i32_16x16x64_i8 v[26:29], v[210:213], v[178:181], v[26:29]
	v_mfma_i32_16x16x64_i8 v[14:17], v[202:205], v[186:189], v[14:17]
	v_mfma_i32_16x16x64_i8 v[10:13], v[210:213], v[186:189], v[10:13]
	v_mfma_i32_16x16x64_i8 v[34:37], v[202:205], v[162:165], v[78:81]
	v_mfma_i32_16x16x64_i8 v[38:41], v[210:213], v[162:165], v[74:77]
	v_mfma_i32_16x16x64_i8 v[42:45], v[202:205], v[170:173], v[62:65]
	v_mfma_i32_16x16x64_i8 v[46:49], v[210:213], v[170:173], v[58:61]
	v_mfma_i32_16x16x64_i8 v[30:33], v[206:209], v[182:185], v[30:33]
	v_mfma_i32_16x16x64_i8 v[26:29], v[214:217], v[182:185], v[26:29]
	v_mfma_i32_16x16x64_i8 v[14:17], v[206:209], v[198:201], v[14:17]
	v_mfma_i32_16x16x64_i8 v[10:13], v[214:217], v[198:201], v[10:13]
	v_mfma_i32_16x16x64_i8 v[34:37], v[206:209], v[166:169], v[34:37]
	v_mfma_i32_16x16x64_i8 v[38:41], v[214:217], v[166:169], v[38:41]
	v_mfma_i32_16x16x64_i8 v[42:45], v[206:209], v[174:177], v[42:45]
	v_mfma_i32_16x16x64_i8 v[46:49], v[214:217], v[174:177], v[46:49]
	s_add_i32 s10, 0, 0x18000
	v_add_u32_e32 v78, s10, v191
	s_barrier
	ds_read_b128 v[58:61], v78
	ds_read_b128 v[62:65], v78 offset:1024
	ds_read_b128 v[74:77], v78 offset:2048
	ds_read_b128 v[78:81], v78 offset:3072
	s_add_u32 s0, s46, 0x44000
	s_addc_u32 s1, s47, 0
	s_mov_b32 m0, s57
	ds_read_b128 v[162:165], v194 offset:32768
	ds_read_b128 v[166:169], v194 offset:33792
	ds_read_b128 v[170:173], v194 offset:34816
	ds_read_b128 v[174:177], v194 offset:35840
	ds_read_b128 v[178:181], v194 offset:36864
	ds_read_b128 v[182:185], v194 offset:37888
	ds_read_b128 v[186:189], v194 offset:38912
	ds_read_b128 v[198:201], v194 offset:39936
	global_load_lds_dwordx4 v146, s[0:1]
	s_mov_b32 m0, s58
	s_nop 0
	global_load_lds_dwordx4 v150, s[0:1]
	s_waitcnt lgkmcnt(8)
	s_barrier
	s_waitcnt lgkmcnt(0)
	s_waitcnt lgkmcnt(0)
	v_mfma_i32_16x16x64_i8 v[134:137], v[58:61], v[162:165], v[134:137]
	v_mfma_i32_16x16x64_i8 v[130:133], v[74:77], v[162:165], v[130:133]
	v_mfma_i32_16x16x64_i8 v[118:121], v[58:61], v[170:173], v[118:121]
	v_mfma_i32_16x16x64_i8 v[114:117], v[74:77], v[170:173], v[114:117]
	v_mfma_i32_16x16x64_i8 v[102:105], v[58:61], v[178:181], v[102:105]
	v_mfma_i32_16x16x64_i8 v[98:101], v[74:77], v[178:181], v[98:101]
	v_mfma_i32_16x16x64_i8 v[86:89], v[58:61], v[186:189], v[86:89]
	v_mfma_i32_16x16x64_i8 v[82:85], v[74:77], v[186:189], v[82:85]
	v_mfma_i32_16x16x64_i8 v[134:137], v[62:65], v[166:169], v[134:137]
	v_mfma_i32_16x16x64_i8 v[130:133], v[78:81], v[166:169], v[130:133]
	v_mfma_i32_16x16x64_i8 v[118:121], v[62:65], v[174:177], v[118:121]
	v_mfma_i32_16x16x64_i8 v[114:117], v[78:81], v[174:177], v[114:117]
	v_mfma_i32_16x16x64_i8 v[102:105], v[62:65], v[182:185], v[102:105]
	v_mfma_i32_16x16x64_i8 v[98:101], v[78:81], v[182:185], v[98:101]
	v_mfma_i32_16x16x64_i8 v[86:89], v[62:65], v[198:201], v[86:89]
	v_mfma_i32_16x16x64_i8 v[82:85], v[78:81], v[198:201], v[82:85]
	s_barrier
	s_add_i32 s11, 0, 0x1c000
	s_add_i32 s0, s10, s54
	v_add_u32_e32 v154, s11, v191
	s_add_u32 s98, s44, 0x80
	s_addc_u32 s99, s45, 0
	s_mov_b32 m0, s0
	ds_read_b128 v[202:205], v154
	ds_read_b128 v[206:209], v154 offset:1024
	ds_read_b128 v[210:213], v154 offset:2048
	ds_read_b128 v[214:217], v154 offset:3072
	global_load_lds_dwordx4 v148, s[98:99]
	s_add_i32 m0, s0, 0x2000
	s_nop 0
	global_load_lds_dwordx4 v152, s[98:99]
	s_barrier
; #define G_STAGE(bufoff, gbase, voff) do { _Pragma("unroll") for (int _i = 0; _i < 2; ++_i) \
;         __builtin_amdgcn_global_load_lds((const unsigned*)((const char*)(gbase) + (voff)[_i]), (LAS unsigned*)(lds + (bufoff) + ldsw + _i * 8192), 16, 0, 0); } while (0)
; #define G_WAIT_V(n) asm volatile("s_waitcnt vmcnt(" #n ")" ::: "memory")
; #define G_WAIT_L(n) asm volatile("s_waitcnt lgkmcnt(" #n ")" ::: "memory")
; #define G_BAR __builtin_amdgcn_s_barrier()
; #define G_SCHED __builtin_amdgcn_sched_barrier(0)
; template <int MODE  , class Epi, class Sched>
; __device__ __forceinline__ void gemm_phase(LAS unsigned char* lds, const GemmDesc g, const Sched& S, const Epi& E) {
;     ...
;             G_BAR; G_WAIT_L(0); G_MMA(0, 1, At, B1); G_BAR;
;             G_LDA(At, 1, 1); G_STAGE(G_SA(1, 0), a3, voffA);
;             G_BAR; G_WAIT_L(0); G_MMA(1, 0, At, B0); G_BAR; G_SCHED;
;             G_STAGE(G_SB(1, 1), b3 + hstepB, voffB);
;             G_WAIT_V(6); G_BAR; G_MMA(1, 1, At, B1); G_BAR;
;         }
	s_waitcnt lgkmcnt(0)
	s_waitcnt lgkmcnt(0)
	v_mfma_i32_16x16x64_i8 v[142:145], v[202:205], v[162:165], v[142:145]
	v_mfma_i32_16x16x64_i8 v[138:141], v[210:213], v[162:165], v[138:141]
	v_mfma_i32_16x16x64_i8 v[126:129], v[202:205], v[170:173], v[126:129]
	v_mfma_i32_16x16x64_i8 v[122:125], v[210:213], v[170:173], v[122:125]
	v_mfma_i32_16x16x64_i8 v[110:113], v[202:205], v[178:181], v[110:113]
	v_mfma_i32_16x16x64_i8 v[106:109], v[210:213], v[178:181], v[106:109]
	v_mfma_i32_16x16x64_i8 v[94:97], v[202:205], v[186:189], v[94:97]
	v_mfma_i32_16x16x64_i8 v[90:93], v[210:213], v[186:189], v[90:93]
	v_mfma_i32_16x16x64_i8 v[142:145], v[206:209], v[166:169], v[142:145]
	v_mfma_i32_16x16x64_i8 v[138:141], v[214:217], v[166:169], v[138:141]
	v_mfma_i32_16x16x64_i8 v[126:129], v[206:209], v[174:177], v[126:129]
	v_mfma_i32_16x16x64_i8 v[122:125], v[214:217], v[174:177], v[122:125]
	v_mfma_i32_16x16x64_i8 v[110:113], v[206:209], v[182:185], v[110:113]
	v_mfma_i32_16x16x64_i8 v[106:109], v[214:217], v[182:185], v[106:109]
	v_mfma_i32_16x16x64_i8 v[94:97], v[206:209], v[198:201], v[94:97]
	v_mfma_i32_16x16x64_i8 v[90:93], v[214:217], v[198:201], v[90:93]
	s_mov_b32 m0, s60
	s_barrier
	ds_read_b128 v[162:165], v194 offset:49152
	ds_read_b128 v[166:169], v194 offset:50176
	ds_read_b128 v[170:173], v194 offset:51200
	ds_read_b128 v[174:177], v194 offset:52224
	ds_read_b128 v[178:181], v194 offset:53248
	ds_read_b128 v[182:185], v194 offset:54272
	ds_read_b128 v[186:189], v194 offset:55296
	ds_read_b128 v[198:201], v194 offset:56320
	s_add_u32 s98, s46, 0x80
	s_addc_u32 s99, s47, 0
	global_load_lds_dwordx4 v146, s[98:99]
	s_mov_b32 m0, s61
	s_nop 0
	global_load_lds_dwordx4 v150, s[98:99]
	s_waitcnt vmcnt(10)
	s_barrier
	s_waitcnt lgkmcnt(0)
	s_waitcnt lgkmcnt(0)
	v_mfma_i32_16x16x64_i8 v[70:73], v[58:61], v[162:165], v[70:73]
	v_mfma_i32_16x16x64_i8 v[66:69], v[74:77], v[162:165], v[66:69]
	v_mfma_i32_16x16x64_i8 v[54:57], v[58:61], v[170:173], v[54:57]
	v_mfma_i32_16x16x64_i8 v[50:53], v[74:77], v[170:173], v[50:53]
	v_mfma_i32_16x16x64_i8 v[22:25], v[58:61], v[178:181], v[22:25]
	v_mfma_i32_16x16x64_i8 v[18:21], v[74:77], v[178:181], v[18:21]
	v_mfma_i32_16x16x64_i8 v[6:9], v[58:61], v[186:189], v[6:9]
	v_mfma_i32_16x16x64_i8 v[2:5], v[74:77], v[186:189], v[2:5]
	v_mfma_i32_16x16x64_i8 v[70:73], v[62:65], v[166:169], v[70:73]
	v_mfma_i32_16x16x64_i8 v[66:69], v[78:81], v[166:169], v[66:69]
	v_mfma_i32_16x16x64_i8 v[54:57], v[62:65], v[174:177], v[54:57]
	v_mfma_i32_16x16x64_i8 v[50:53], v[78:81], v[174:177], v[50:53]
	v_mfma_i32_16x16x64_i8 v[22:25], v[62:65], v[182:185], v[22:25]
	v_mfma_i32_16x16x64_i8 v[18:21], v[78:81], v[182:185], v[18:21]
	v_mfma_i32_16x16x64_i8 v[6:9], v[62:65], v[198:201], v[6:9]
	v_mfma_i32_16x16x64_i8 v[2:5], v[78:81], v[198:201], v[2:5]
	s_barrier
	ds_read_b128 v[232:235], v193
	ds_read_b128 v[236:239], v193 offset:1024
	ds_read_b128 v[240:243], v193 offset:2048
	ds_read_b128 v[244:247], v193 offset:3072
	s_add_u32 s0, s44, 0x44080
	s_addc_u32 s1, s45, 0
	s_add_i32 s10, s11, s54
	s_mov_b32 m0, s10
	s_nop 0
	global_load_lds_dwordx4 v148, s[0:1]
	s_add_i32 m0, s10, 0x2000
	s_nop 0
	global_load_lds_dwordx4 v152, s[0:1]
	s_waitcnt vmcnt(6)
	s_barrier
	v_mfma_i32_16x16x64_i8 v[34:37], v[202:205], v[162:165], v[34:37]
	s_add_i32 s77, s77, 2
	s_add_u32 s72, s72, 0x100
	s_addc_u32 s76, s76, 0
	s_cmp_gt_u32 s77, 13
	s_mov_b64 s[34:35], s[40:41]
	v_mfma_i32_16x16x64_i8 v[78:81], v[206:209], v[166:169], v[34:37]
	v_mfma_i32_16x16x64_i8 v[34:37], v[210:213], v[162:165], v[38:41]
	v_mfma_i32_16x16x64_i8 v[74:77], v[214:217], v[166:169], v[34:37]
	v_mfma_i32_16x16x64_i8 v[34:37], v[202:205], v[170:173], v[42:45]
	v_mfma_i32_16x16x64_i8 v[62:65], v[206:209], v[174:177], v[34:37]
	v_mfma_i32_16x16x64_i8 v[34:37], v[210:213], v[170:173], v[46:49]
	v_mfma_i32_16x16x64_i8 v[30:33], v[202:205], v[178:181], v[30:33]
	v_mfma_i32_16x16x64_i8 v[26:29], v[210:213], v[178:181], v[26:29]
	v_mfma_i32_16x16x64_i8 v[14:17], v[202:205], v[186:189], v[14:17]
	v_mfma_i32_16x16x64_i8 v[10:13], v[210:213], v[186:189], v[10:13]
	v_mfma_i32_16x16x64_i8 v[58:61], v[214:217], v[174:177], v[34:37]
	v_mfma_i32_16x16x64_i8 v[30:33], v[206:209], v[182:185], v[30:33]
	v_mfma_i32_16x16x64_i8 v[26:29], v[214:217], v[182:185], v[26:29]
	v_mfma_i32_16x16x64_i8 v[14:17], v[206:209], v[198:201], v[14:17]
	v_mfma_i32_16x16x64_i8 v[10:13], v[214:217], v[198:201], v[10:13]
	s_cbranch_scc1 .Lkdone_p1c
	s_barrier
	s_branch .LBB0_527

; #define G_STAGE(bufoff, gbase, voff) do { _Pragma("unroll") for (int _i = 0; _i < 2; ++_i) \
;         __builtin_amdgcn_global_load_lds((const unsigned*)((const char*)(gbase) + (voff)[_i]), (LAS unsigned*)(lds + (bufoff) + ldsw + _i * 8192), 16, 0, 0); } while (0)
; #define G_WAIT_V(n) asm volatile("s_waitcnt vmcnt(" #n ")" ::: "memory")
; #define G_WAIT_L(n) asm volatile("s_waitcnt lgkmcnt(" #n ")" ::: "memory")
; #define G_BAR __builtin_amdgcn_s_barrier()
; #define G_SCHED __builtin_amdgcn_sched_barrier(0)
; template <int MODE  , class Epi, class Sched>
; __device__ __forceinline__ void gemm_phase(LAS unsigned char* lds, const GemmDesc g, const Sched& S, const Epi& E) {
;     ...
;             G_LDB(B0, 0, 0); G_SCHED; G_LDA(At, 0, 0); G_STAGE(G_SA(1, 1), a1 + hstepA, voffA);
;             G_WAIT_L(8); G_BAR; G_WAIT_L(0); G_MMA(0, 0, At, B0); G_BAR; G_SCHED;
;             G_LDB(B1, 0, 1); G_STAGE(G_SB(0, 0), b2, voffB);
;             G_BAR; G_WAIT_L(0); G_MMA(0, 1, At, B1); G_BAR;
;             G_LDA(At, 0, 1); G_STAGE(G_SA(0, 0), a2, voffA);
;             G_BAR; G_WAIT_L(0); G_MMA(1, 0, At, B0); G_BAR; G_SCHED;
;             G_STAGE(G_SB(0, 1), b2 + hstepB, voffB);
;             G_WAIT_V(6); G_BAR; G_MMA(1, 1, At, B1); G_BAR;
;             G_LDB(B0, 1, 0); G_SCHED; G_LDA(At, 1, 0); G_STAGE(G_SA(0, 1), a2 + hstepA, voffA);
;             G_WAIT_L(8); G_BAR; G_WAIT_L(0); G_MMA(0, 0, At, B0); G_BAR; G_SCHED;
;             G_LDB(B1, 1, 1); G_STAGE(G_SB(1, 0), b3, voffB);
.Lnodb_p1b:
.LBB0_737:
	ds_read_b128 v[2:5], v168
	ds_read_b128 v[6:9], v168 offset:1024
	ds_read_b128 v[10:13], v168 offset:2048
	ds_read_b128 v[14:17], v168 offset:3072
	s_add_u32 s46, s50, 0x100
	s_addc_u32 s47, s51, 0
	s_cmp_eq_u32 s79, 12
	s_cselect_b32 s55, s45, s47
	s_cselect_b32 s54, s44, s46
	s_cselect_b32 s53, s3, s78
	s_cselect_b32 s52, s2, s77
	s_add_u32 s98, s50, 0x44080
	s_addc_u32 s99, s51, 0
	s_add_i32 m0, s62, 0xc000
	ds_read_b128 v[174:177], v169
	ds_read_b128 v[178:181], v169 offset:1024
	ds_read_b128 v[182:185], v169 offset:2048
	ds_read_b128 v[186:189], v169 offset:3072
	ds_read_b128 v[192:195], v169 offset:4096
	ds_read_b128 v[196:199], v169 offset:5120
	ds_read_b128 v[200:203], v169 offset:6144
	ds_read_b128 v[204:207], v169 offset:7168
	global_load_lds_dwordx4 v152, s[98:99]
	s_add_i32 m0, s62, 0xe000
	s_nop 0
	global_load_lds_dwordx4 v148, s[98:99]
	s_waitcnt lgkmcnt(8)
	s_barrier
	s_waitcnt lgkmcnt(0)
	s_waitcnt lgkmcnt(0)
	v_mfma_scale_f32_16x16x128_f8f6f4 v[142:145], v[2:9], v[174:181], v[142:145], v170, v170 op_sel_hi:[0,0,0]
	v_mfma_scale_f32_16x16x128_f8f6f4 v[138:141], v[10:17], v[174:181], v[138:141], v170, v170 op_sel_hi:[0,0,0]
	v_mfma_scale_f32_16x16x128_f8f6f4 v[126:129], v[2:9], v[182:189], v[126:129], v170, v170 op_sel_hi:[0,0,0]
	v_mfma_scale_f32_16x16x128_f8f6f4 v[122:125], v[10:17], v[182:189], v[122:125], v170, v170 op_sel_hi:[0,0,0]
	v_mfma_scale_f32_16x16x128_f8f6f4 v[110:113], v[2:9], v[192:199], v[110:113], v170, v170 op_sel_hi:[0,0,0]
	v_mfma_scale_f32_16x16x128_f8f6f4 v[106:109], v[10:17], v[192:199], v[106:109], v170, v170 op_sel_hi:[0,0,0]
	v_mfma_scale_f32_16x16x128_f8f6f4 v[94:97], v[2:9], v[200:207], v[94:97], v170, v170 op_sel_hi:[0,0,0]
	v_mfma_scale_f32_16x16x128_f8f6f4 v[90:93], v[10:17], v[200:207], v[90:93], v170, v170 op_sel_hi:[0,0,0]
	s_barrier
	s_add_i32 s0, s69, s60
	s_mov_b32 m0, s0
	ds_read_b128 v[208:211], v171
	ds_read_b128 v[212:215], v171 offset:1024
	ds_read_b128 v[216:219], v171 offset:2048
	ds_read_b128 v[220:223], v171 offset:3072
	global_load_lds_dwordx4 v150, s[52:53]
	s_add_i32 m0, s0, 0x2000
	s_nop 0
	global_load_lds_dwordx4 v146, s[52:53]
	s_barrier
	s_waitcnt lgkmcnt(0)
	s_waitcnt lgkmcnt(0)
	v_mfma_scale_f32_16x16x128_f8f6f4 v[134:137], v[208:215], v[174:181], v[134:137], v170, v170 op_sel_hi:[0,0,0]
	v_mfma_scale_f32_16x16x128_f8f6f4 v[130:133], v[216:223], v[174:181], v[130:133], v170, v170 op_sel_hi:[0,0,0]
	v_mfma_scale_f32_16x16x128_f8f6f4 v[118:121], v[208:215], v[182:189], v[118:121], v170, v170 op_sel_hi:[0,0,0]
	v_mfma_scale_f32_16x16x128_f8f6f4 v[114:117], v[216:223], v[182:189], v[114:117], v170, v170 op_sel_hi:[0,0,0]
	v_mfma_scale_f32_16x16x128_f8f6f4 v[102:105], v[208:215], v[192:199], v[102:105], v170, v170 op_sel_hi:[0,0,0]
	v_mfma_scale_f32_16x16x128_f8f6f4 v[98:101], v[216:223], v[192:199], v[98:101], v170, v170 op_sel_hi:[0,0,0]
	v_mfma_scale_f32_16x16x128_f8f6f4 v[86:89], v[208:215], v[200:207], v[86:89], v170, v170 op_sel_hi:[0,0,0]
	v_mfma_scale_f32_16x16x128_f8f6f4 v[82:85], v[216:223], v[200:207], v[82:85], v170, v170 op_sel_hi:[0,0,0]
	s_mov_b32 m0, s62
	s_barrier
	ds_read_b128 v[174:177], v169 offset:16384
	ds_read_b128 v[178:181], v169 offset:17408
	ds_read_b128 v[182:185], v169 offset:18432
	ds_read_b128 v[186:189], v169 offset:19456
	ds_read_b128 v[192:195], v169 offset:20480
	ds_read_b128 v[196:199], v169 offset:21504
	ds_read_b128 v[200:203], v169 offset:22528
	ds_read_b128 v[204:207], v169 offset:23552
	global_load_lds_dwordx4 v152, s[54:55]
	s_mov_b32 m0, s63
	s_nop 0
	global_load_lds_dwordx4 v148, s[54:55]
	s_barrier
	s_waitcnt lgkmcnt(0)
	s_waitcnt lgkmcnt(0)
	v_mfma_scale_f32_16x16x128_f8f6f4 v[78:81], v[2:9], v[174:181], v[78:81], v170, v170 op_sel_hi:[0,0,0]
	v_mfma_scale_f32_16x16x128_f8f6f4 v[74:77], v[10:17], v[174:181], v[74:77], v170, v170 op_sel_hi:[0,0,0]
	v_mfma_scale_f32_16x16x128_f8f6f4 v[62:65], v[2:9], v[182:189], v[62:65], v170, v170 op_sel_hi:[0,0,0]
	v_mfma_scale_f32_16x16x128_f8f6f4 v[58:61], v[10:17], v[182:189], v[58:61], v170, v170 op_sel_hi:[0,0,0]
	v_mfma_scale_f32_16x16x128_f8f6f4 v[46:49], v[2:9], v[192:199], v[46:49], v170, v170 op_sel_hi:[0,0,0]
	v_mfma_scale_f32_16x16x128_f8f6f4 v[42:45], v[10:17], v[192:199], v[42:45], v170, v170 op_sel_hi:[0,0,0]
	v_mfma_scale_f32_16x16x128_f8f6f4 v[30:33], v[2:9], v[200:207], v[30:33], v170, v170 op_sel_hi:[0,0,0]
	v_mfma_scale_f32_16x16x128_f8f6f4 v[26:29], v[10:17], v[200:207], v[26:29], v170, v170 op_sel_hi:[0,0,0]
	s_barrier
	s_add_u32 s0, s52, 0x44000
	s_addc_u32 s1, s53, 0
	s_add_i32 s10, s70, s60
	s_mov_b32 m0, s10
	s_nop 0
	global_load_lds_dwordx4 v150, s[0:1]
	s_add_i32 m0, s10, 0x2000
	s_nop 0
	global_load_lds_dwordx4 v146, s[0:1]
	s_waitcnt vmcnt(6)
	s_barrier
	v_mfma_scale_f32_16x16x128_f8f6f4 v[70:73], v[208:215], v[174:181], v[70:73], v170, v170 op_sel_hi:[0,0,0]
	v_mfma_scale_f32_16x16x128_f8f6f4 v[66:69], v[216:223], v[174:181], v[66:69], v170, v170 op_sel_hi:[0,0,0]
	v_mfma_scale_f32_16x16x128_f8f6f4 v[54:57], v[208:215], v[182:189], v[54:57], v170, v170 op_sel_hi:[0,0,0]
	v_mfma_scale_f32_16x16x128_f8f6f4 v[50:53], v[216:223], v[182:189], v[50:53], v170, v170 op_sel_hi:[0,0,0]
	v_mfma_scale_f32_16x16x128_f8f6f4 v[38:41], v[208:215], v[192:199], v[38:41], v170, v170 op_sel_hi:[0,0,0]
	v_mfma_scale_f32_16x16x128_f8f6f4 v[34:37], v[216:223], v[192:199], v[34:37], v170, v170 op_sel_hi:[0,0,0]
	v_mfma_scale_f32_16x16x128_f8f6f4 v[22:25], v[208:215], v[200:207], v[22:25], v170, v170 op_sel_hi:[0,0,0]
	v_mfma_scale_f32_16x16x128_f8f6f4 v[18:21], v[216:223], v[200:207], v[18:21], v170, v170 op_sel_hi:[0,0,0]
	s_add_i32 s10, 0, 0x18000
	v_add_u32_e32 v14, s10, v166
	s_barrier
; #define G_STAGE(bufoff, gbase, voff) do { _Pragma("unroll") for (int _i = 0; _i < 2; ++_i) \
;         __builtin_amdgcn_global_load_lds((const unsigned*)((const char*)(gbase) + (voff)[_i]), (LAS unsigned*)(lds + (bufoff) + ldsw + _i * 8192), 16, 0, 0); } while (0)
; #define G_WAIT_V(n) asm volatile("s_waitcnt vmcnt(" #n ")" ::: "memory")
; #define G_WAIT_L(n) asm volatile("s_waitcnt lgkmcnt(" #n ")" ::: "memory")
; #define G_BAR __builtin_amdgcn_s_barrier()
; #define G_SCHED __builtin_amdgcn_sched_barrier(0)
; template <int MODE  , class Epi, class Sched>
; __device__ __forceinline__ void gemm_phase(LAS unsigned char* lds, const GemmDesc g, const Sched& S, const Epi& E) {
;     ...
;             G_LDB(B1, 1, 1); G_STAGE(G_SB(1, 0), b3, voffB);
;             G_BAR; G_WAIT_L(0); G_MMA(0, 1, At, B1); G_BAR;
;             G_LDA(At, 1, 1); G_STAGE(G_SA(1, 0), a3, voffA);
;             G_BAR; G_WAIT_L(0); G_MMA(1, 0, At, B0); G_BAR; G_SCHED;
;             G_STAGE(G_SB(1, 1), b3 + hstepB, voffB);
;             G_WAIT_V(6); G_BAR; G_MMA(1, 1, At, B1); G_BAR;
;         }
	ds_read_b128 v[2:5], v14
	ds_read_b128 v[6:9], v14 offset:1024
	ds_read_b128 v[10:13], v14 offset:2048
	ds_read_b128 v[14:17], v14 offset:3072
	s_add_u32 s0, s54, 0x44000
	s_addc_u32 s1, s55, 0
	s_mov_b32 m0, s64
	ds_read_b128 v[174:177], v169 offset:32768
	ds_read_b128 v[178:181], v169 offset:33792
	ds_read_b128 v[182:185], v169 offset:34816
	ds_read_b128 v[186:189], v169 offset:35840
	ds_read_b128 v[192:195], v169 offset:36864
	ds_read_b128 v[196:199], v169 offset:37888
	ds_read_b128 v[200:203], v169 offset:38912
	ds_read_b128 v[204:207], v169 offset:39936
	global_load_lds_dwordx4 v152, s[0:1]
	s_mov_b32 m0, s65
	s_nop 0
	global_load_lds_dwordx4 v148, s[0:1]
	s_waitcnt lgkmcnt(8)
	s_barrier
	s_waitcnt lgkmcnt(0)
	s_waitcnt lgkmcnt(0)
	v_mfma_scale_f32_16x16x128_f8f6f4 v[142:145], v[2:9], v[174:181], v[142:145], v170, v170 op_sel_hi:[0,0,0]
	v_mfma_scale_f32_16x16x128_f8f6f4 v[138:141], v[10:17], v[174:181], v[138:141], v170, v170 op_sel_hi:[0,0,0]
	v_mfma_scale_f32_16x16x128_f8f6f4 v[126:129], v[2:9], v[182:189], v[126:129], v170, v170 op_sel_hi:[0,0,0]
	v_mfma_scale_f32_16x16x128_f8f6f4 v[122:125], v[10:17], v[182:189], v[122:125], v170, v170 op_sel_hi:[0,0,0]
	v_mfma_scale_f32_16x16x128_f8f6f4 v[110:113], v[2:9], v[192:199], v[110:113], v170, v170 op_sel_hi:[0,0,0]
	v_mfma_scale_f32_16x16x128_f8f6f4 v[106:109], v[10:17], v[192:199], v[106:109], v170, v170 op_sel_hi:[0,0,0]
	v_mfma_scale_f32_16x16x128_f8f6f4 v[94:97], v[2:9], v[200:207], v[94:97], v170, v170 op_sel_hi:[0,0,0]
	v_mfma_scale_f32_16x16x128_f8f6f4 v[90:93], v[10:17], v[200:207], v[90:93], v170, v170 op_sel_hi:[0,0,0]
	s_barrier
	s_add_i32 s11, 0, 0x1c000
	s_add_i32 s0, s10, s60
	v_add_u32_e32 v173, s11, v166
	s_add_u32 s98, s52, 0x80
	s_addc_u32 s99, s53, 0
	s_mov_b32 m0, s0
	ds_read_b128 v[208:211], v173
	ds_read_b128 v[212:215], v173 offset:1024
	ds_read_b128 v[216:219], v173 offset:2048
	ds_read_b128 v[220:223], v173 offset:3072
	global_load_lds_dwordx4 v150, s[98:99]
	s_add_i32 m0, s0, 0x2000
	s_nop 0
	global_load_lds_dwordx4 v146, s[98:99]
	s_barrier
	s_waitcnt lgkmcnt(0)
	s_waitcnt lgkmcnt(0)
	v_mfma_scale_f32_16x16x128_f8f6f4 v[134:137], v[208:215], v[174:181], v[134:137], v170, v170 op_sel_hi:[0,0,0]
	v_mfma_scale_f32_16x16x128_f8f6f4 v[130:133], v[216:223], v[174:181], v[130:133], v170, v170 op_sel_hi:[0,0,0]
	v_mfma_scale_f32_16x16x128_f8f6f4 v[118:121], v[208:215], v[182:189], v[118:121], v170, v170 op_sel_hi:[0,0,0]
	v_mfma_scale_f32_16x16x128_f8f6f4 v[114:117], v[216:223], v[182:189], v[114:117], v170, v170 op_sel_hi:[0,0,0]
	v_mfma_scale_f32_16x16x128_f8f6f4 v[102:105], v[208:215], v[192:199], v[102:105], v170, v170 op_sel_hi:[0,0,0]
	v_mfma_scale_f32_16x16x128_f8f6f4 v[98:101], v[216:223], v[192:199], v[98:101], v170, v170 op_sel_hi:[0,0,0]
	v_mfma_scale_f32_16x16x128_f8f6f4 v[86:89], v[208:215], v[200:207], v[86:89], v170, v170 op_sel_hi:[0,0,0]
	v_mfma_scale_f32_16x16x128_f8f6f4 v[82:85], v[216:223], v[200:207], v[82:85], v170, v170 op_sel_hi:[0,0,0]
	s_mov_b32 m0, s67
	s_add_u32 s98, s54, 0x80
	s_addc_u32 s99, s55, 0
	s_barrier
	ds_read_b128 v[174:177], v169 offset:49152
	ds_read_b128 v[178:181], v169 offset:50176
	ds_read_b128 v[182:185], v169 offset:51200
	ds_read_b128 v[186:189], v169 offset:52224
	ds_read_b128 v[192:195], v169 offset:53248
	ds_read_b128 v[196:199], v169 offset:54272
	ds_read_b128 v[200:203], v169 offset:55296
	ds_read_b128 v[204:207], v169 offset:56320
	global_load_lds_dwordx4 v152, s[98:99]
	s_mov_b32 m0, s68
	s_nop 0
	global_load_lds_dwordx4 v148, s[98:99]
	s_barrier
	s_waitcnt lgkmcnt(0)
	s_waitcnt lgkmcnt(0)
	v_mfma_scale_f32_16x16x128_f8f6f4 v[78:81], v[2:9], v[174:181], v[78:81], v170, v170 op_sel_hi:[0,0,0]
	v_mfma_scale_f32_16x16x128_f8f6f4 v[74:77], v[10:17], v[174:181], v[74:77], v170, v170 op_sel_hi:[0,0,0]
	v_mfma_scale_f32_16x16x128_f8f6f4 v[62:65], v[2:9], v[182:189], v[62:65], v170, v170 op_sel_hi:[0,0,0]
	v_mfma_scale_f32_16x16x128_f8f6f4 v[58:61], v[10:17], v[182:189], v[58:61], v170, v170 op_sel_hi:[0,0,0]
	v_mfma_scale_f32_16x16x128_f8f6f4 v[46:49], v[2:9], v[192:199], v[46:49], v170, v170 op_sel_hi:[0,0,0]
	v_mfma_scale_f32_16x16x128_f8f6f4 v[42:45], v[10:17], v[192:199], v[42:45], v170, v170 op_sel_hi:[0,0,0]
	v_mfma_scale_f32_16x16x128_f8f6f4 v[30:33], v[2:9], v[200:207], v[30:33], v170, v170 op_sel_hi:[0,0,0]
	v_mfma_scale_f32_16x16x128_f8f6f4 v[26:29], v[10:17], v[200:207], v[26:29], v170, v170 op_sel_hi:[0,0,0]
	s_barrier
	s_add_u32 s0, s52, 0x44080
	s_addc_u32 s1, s53, 0
	s_add_i32 s10, s11, s60
	s_mov_b32 m0, s10
	s_nop 0
	global_load_lds_dwordx4 v150, s[0:1]
	s_add_i32 m0, s10, 0x2000
	s_nop 0
	global_load_lds_dwordx4 v146, s[0:1]
	s_waitcnt vmcnt(6)
	s_barrier
	v_mfma_scale_f32_16x16x128_f8f6f4 v[70:73], v[208:215], v[174:181], v[70:73], v170, v170 op_sel_hi:[0,0,0]
	s_add_i32 s79, s79, 2
	s_add_u32 s77, s77, 0x100
	s_addc_u32 s78, s78, 0
	s_cmp_gt_u32 s79, 13
	s_mov_b64 s[50:51], s[46:47]
	v_mfma_scale_f32_16x16x128_f8f6f4 v[66:69], v[216:223], v[174:181], v[66:69], v170, v170 op_sel_hi:[0,0,0]
	v_mfma_scale_f32_16x16x128_f8f6f4 v[54:57], v[208:215], v[182:189], v[54:57], v170, v170 op_sel_hi:[0,0,0]
	v_mfma_scale_f32_16x16x128_f8f6f4 v[50:53], v[216:223], v[182:189], v[50:53], v170, v170 op_sel_hi:[0,0,0]
	v_mfma_scale_f32_16x16x128_f8f6f4 v[38:41], v[208:215], v[192:199], v[38:41], v170, v170 op_sel_hi:[0,0,0]
	v_mfma_scale_f32_16x16x128_f8f6f4 v[34:37], v[216:223], v[192:199], v[34:37], v170, v170 op_sel_hi:[0,0,0]
	v_mfma_scale_f32_16x16x128_f8f6f4 v[22:25], v[208:215], v[200:207], v[22:25], v170, v170 op_sel_hi:[0,0,0]
	v_mfma_scale_f32_16x16x128_f8f6f4 v[18:21], v[216:223], v[200:207], v[18:21], v170, v170 op_sel_hi:[0,0,0]
	s_cbranch_scc1 .Lkdone_p1b
	s_barrier
	s_branch .LBB0_737

; #define G_STAGE(bufoff, gbase, voff) do { _Pragma("unroll") for (int _i = 0; _i < 2; ++_i) \
;         __builtin_amdgcn_global_load_lds((const unsigned*)((const char*)(gbase) + (voff)[_i]), (LAS unsigned*)(lds + (bufoff) + ldsw + _i * 8192), 16, 0, 0); } while (0)
; #define G_WAIT_V(n) asm volatile("s_waitcnt vmcnt(" #n ")" ::: "memory")
; #define G_WAIT_L(n) asm volatile("s_waitcnt lgkmcnt(" #n ")" ::: "memory")
; #define G_BAR __builtin_amdgcn_s_barrier()
; #define G_SCHED __builtin_amdgcn_sched_barrier(0)
; template <int MODE  , class Epi, class Sched>
; __device__ __forceinline__ void gemm_phase(LAS unsigned char* lds, const GemmDesc g, const Sched& S, const Epi& E) {
;     ...
;             G_LDB(B0, 0, 0); G_SCHED; G_LDA(At, 0, 0); G_STAGE(G_SA(1, 1), a1 + hstepA, voffA);
;             G_WAIT_L(8); G_BAR; G_WAIT_L(0); G_MMA(0, 0, At, B0); G_BAR; G_SCHED;
;             G_LDB(B1, 0, 1); G_STAGE(G_SB(0, 0), b2, voffB);
;             G_BAR; G_WAIT_L(0); G_MMA(0, 1, At, B1); G_BAR;
;             G_LDA(At, 0, 1); G_STAGE(G_SA(0, 0), a2, voffA);
;             G_BAR; G_WAIT_L(0); G_MMA(1, 0, At, B0); G_BAR; G_SCHED;
;             G_STAGE(G_SB(0, 1), b2 + hstepB, voffB);
;             G_WAIT_V(6); G_BAR; G_MMA(1, 1, At, B1); G_BAR;
.Lnodb_sa:
.LBB0_815:
	v_add_u32_e32 v142, s58, v172
	ds_read_b128 v[130:133], v142
	ds_read_b128 v[134:137], v142 offset:1024
	ds_read_b128 v[138:141], v142 offset:2048
	ds_read_b128 v[142:145], v142 offset:3072
	s_add_u32 s44, s42, 0x100
	s_addc_u32 s45, s43, 0
	s_cmp_eq_u32 s68, 12
	s_cselect_b32 s49, s35, s45
	s_cselect_b32 s48, s34, s44
	s_cselect_b32 s47, s3, s67
	s_cselect_b32 s46, s2, s21
	s_add_u32 s98, s42, 0x84080
	s_addc_u32 s99, s43, 0
	s_add_i32 m0, s52, 0xc000
	ds_read_b128 v[158:161], v174
	ds_read_b128 v[162:165], v174 offset:1024
	ds_read_b128 v[166:169], v174 offset:2048
	ds_read_b128 v[176:179], v174 offset:3072
	ds_read_b128 v[180:183], v174 offset:4096
	ds_read_b128 v[184:187], v174 offset:5120
	ds_read_b128 v[192:195], v174 offset:6144
	ds_read_b128 v[196:199], v174 offset:7168
	global_load_lds_dwordx4 v146, s[98:99]
	s_add_i32 m0, s52, 0xe000
	s_nop 0
	global_load_lds_dwordx4 v150, s[98:99]
	s_waitcnt lgkmcnt(8)
	s_barrier
	s_waitcnt lgkmcnt(0)
	s_waitcnt lgkmcnt(0)
	v_mfma_f32_16x16x32_bf16 v[126:129], v[130:133], v[158:161], v[126:129]
	v_mfma_f32_16x16x32_bf16 v[122:125], v[138:141], v[158:161], v[122:125]
	v_mfma_f32_16x16x32_bf16 v[118:121], v[130:133], v[166:169], v[118:121]
	v_mfma_f32_16x16x32_bf16 v[114:117], v[138:141], v[166:169], v[114:117]
	v_mfma_f32_16x16x32_bf16 v[110:113], v[130:133], v[180:183], v[110:113]
	v_mfma_f32_16x16x32_bf16 v[106:109], v[138:141], v[180:183], v[106:109]
	v_mfma_f32_16x16x32_bf16 v[102:105], v[130:133], v[192:195], v[102:105]
	v_mfma_f32_16x16x32_bf16 v[98:101], v[138:141], v[192:195], v[98:101]
	v_mfma_f32_16x16x32_bf16 v[126:129], v[134:137], v[162:165], v[126:129]
	v_mfma_f32_16x16x32_bf16 v[122:125], v[142:145], v[162:165], v[122:125]
	v_mfma_f32_16x16x32_bf16 v[118:121], v[134:137], v[176:179], v[118:121]
	v_mfma_f32_16x16x32_bf16 v[114:117], v[142:145], v[176:179], v[114:117]
	v_mfma_f32_16x16x32_bf16 v[110:113], v[134:137], v[184:187], v[110:113]
	v_mfma_f32_16x16x32_bf16 v[106:109], v[142:145], v[184:187], v[106:109]
	v_mfma_f32_16x16x32_bf16 v[102:105], v[134:137], v[196:199], v[102:105]
	v_mfma_f32_16x16x32_bf16 v[98:101], v[142:145], v[196:199], v[98:101]
	s_barrier
	v_add_u32_e32 v170, s59, v172
	s_add_i32 s0, s58, s51
	ds_read_b128 v[200:203], v170
	ds_read_b128 v[204:207], v170 offset:1024
	ds_read_b128 v[208:211], v170 offset:2048
	ds_read_b128 v[212:215], v170 offset:3072
	s_mov_b32 m0, s0
	s_nop 0
	global_load_lds_dwordx4 v148, s[46:47]
	s_add_i32 m0, s0, 0x2000
	s_nop 0
	global_load_lds_dwordx4 v152, s[46:47]
	s_barrier
	s_waitcnt lgkmcnt(0)
	s_waitcnt lgkmcnt(0)
	v_mfma_f32_16x16x32_bf16 v[94:97], v[200:203], v[158:161], v[94:97]
	v_mfma_f32_16x16x32_bf16 v[90:93], v[208:211], v[158:161], v[90:93]
	v_mfma_f32_16x16x32_bf16 v[86:89], v[200:203], v[166:169], v[86:89]
	v_mfma_f32_16x16x32_bf16 v[82:85], v[208:211], v[166:169], v[82:85]
	v_mfma_f32_16x16x32_bf16 v[78:81], v[200:203], v[180:183], v[78:81]
	v_mfma_f32_16x16x32_bf16 v[74:77], v[208:211], v[180:183], v[74:77]
	v_mfma_f32_16x16x32_bf16 v[70:73], v[200:203], v[192:195], v[70:73]
	v_mfma_f32_16x16x32_bf16 v[66:69], v[208:211], v[192:195], v[66:69]
	v_mfma_f32_16x16x32_bf16 v[94:97], v[204:207], v[162:165], v[94:97]
	v_mfma_f32_16x16x32_bf16 v[90:93], v[212:215], v[162:165], v[90:93]
	v_mfma_f32_16x16x32_bf16 v[86:89], v[204:207], v[176:179], v[86:89]
	v_mfma_f32_16x16x32_bf16 v[82:85], v[212:215], v[176:179], v[82:85]
	v_mfma_f32_16x16x32_bf16 v[78:81], v[204:207], v[184:187], v[78:81]
	v_mfma_f32_16x16x32_bf16 v[74:77], v[212:215], v[184:187], v[74:77]
	v_mfma_f32_16x16x32_bf16 v[70:73], v[204:207], v[196:199], v[70:73]
	v_mfma_f32_16x16x32_bf16 v[66:69], v[212:215], v[196:199], v[66:69]
	s_mov_b32 m0, s52
	s_barrier
	ds_read_b128 v[158:161], v174 offset:16384
	ds_read_b128 v[162:165], v174 offset:17408
	ds_read_b128 v[166:169], v174 offset:18432
	ds_read_b128 v[176:179], v174 offset:19456
	ds_read_b128 v[180:183], v174 offset:20480
	ds_read_b128 v[184:187], v174 offset:21504
	ds_read_b128 v[192:195], v174 offset:22528
	ds_read_b128 v[196:199], v174 offset:23552
	global_load_lds_dwordx4 v146, s[48:49]
	s_mov_b32 m0, s53
	s_nop 0
	global_load_lds_dwordx4 v150, s[48:49]
	s_barrier
	s_waitcnt lgkmcnt(0)
	s_waitcnt lgkmcnt(0)
	v_mfma_f32_16x16x32_bf16 v[62:65], v[130:133], v[158:161], v[62:65]
	v_mfma_f32_16x16x32_bf16 v[58:61], v[138:141], v[158:161], v[58:61]
	v_mfma_f32_16x16x32_bf16 v[54:57], v[130:133], v[166:169], v[54:57]
	v_mfma_f32_16x16x32_bf16 v[50:53], v[138:141], v[166:169], v[50:53]
	v_mfma_f32_16x16x32_bf16 v[46:49], v[130:133], v[180:183], v[46:49]
	v_mfma_f32_16x16x32_bf16 v[42:45], v[138:141], v[180:183], v[42:45]
	v_mfma_f32_16x16x32_bf16 v[38:41], v[130:133], v[192:195], v[38:41]
	v_mfma_f32_16x16x32_bf16 v[34:37], v[138:141], v[192:195], v[34:37]
	v_mfma_f32_16x16x32_bf16 v[62:65], v[134:137], v[162:165], v[62:65]
	v_mfma_f32_16x16x32_bf16 v[58:61], v[142:145], v[162:165], v[58:61]
	v_mfma_f32_16x16x32_bf16 v[54:57], v[134:137], v[176:179], v[54:57]
	v_mfma_f32_16x16x32_bf16 v[50:53], v[142:145], v[176:179], v[50:53]
	v_mfma_f32_16x16x32_bf16 v[46:49], v[134:137], v[184:187], v[46:49]
	v_mfma_f32_16x16x32_bf16 v[42:45], v[142:145], v[184:187], v[42:45]
	v_mfma_f32_16x16x32_bf16 v[38:41], v[134:137], v[196:199], v[38:41]
	v_mfma_f32_16x16x32_bf16 v[34:37], v[142:145], v[196:199], v[34:37]
	s_barrier
	s_add_u32 s0, s46, 0x84000
	s_addc_u32 s1, s47, 0
	s_add_i32 s10, s59, s51
	s_mov_b32 m0, s10
	s_nop 0
	global_load_lds_dwordx4 v148, s[0:1]
	s_add_i32 m0, s10, 0x2000
	s_nop 0
	global_load_lds_dwordx4 v152, s[0:1]
	s_waitcnt vmcnt(6)
	s_barrier
; #define G_STAGE(bufoff, gbase, voff) do { _Pragma("unroll") for (int _i = 0; _i < 2; ++_i) \
;         __builtin_amdgcn_global_load_lds((const unsigned*)((const char*)(gbase) + (voff)[_i]), (LAS unsigned*)(lds + (bufoff) + ldsw + _i * 8192), 16, 0, 0); } while (0)
; #define G_WAIT_V(n) asm volatile("s_waitcnt vmcnt(" #n ")" ::: "memory")
; #define G_WAIT_L(n) asm volatile("s_waitcnt lgkmcnt(" #n ")" ::: "memory")
; #define G_BAR __builtin_amdgcn_s_barrier()
; #define G_SCHED __builtin_amdgcn_sched_barrier(0)
; template <int MODE  , class Epi, class Sched>
; __device__ __forceinline__ void gemm_phase(LAS unsigned char* lds, const GemmDesc g, const Sched& S, const Epi& E) {
;     ...
;             G_WAIT_V(6); G_BAR; G_MMA(1, 1, At, B1); G_BAR;
;             G_LDB(B0, 1, 0); G_SCHED; G_LDA(At, 1, 0); G_STAGE(G_SA(0, 1), a2 + hstepA, voffA);
;             G_WAIT_L(8); G_BAR; G_WAIT_L(0); G_MMA(0, 0, At, B0); G_BAR; G_SCHED;
;             G_LDB(B1, 1, 1); G_STAGE(G_SB(1, 0), b3, voffB);
	v_mfma_f32_16x16x32_bf16 v[30:33], v[200:203], v[158:161], v[30:33]
	v_mfma_f32_16x16x32_bf16 v[26:29], v[208:211], v[158:161], v[26:29]
	v_mfma_f32_16x16x32_bf16 v[22:25], v[200:203], v[166:169], v[22:25]
	v_mfma_f32_16x16x32_bf16 v[18:21], v[208:211], v[166:169], v[18:21]
	v_mfma_f32_16x16x32_bf16 v[14:17], v[200:203], v[180:183], v[14:17]
	v_mfma_f32_16x16x32_bf16 v[10:13], v[208:211], v[180:183], v[10:13]
	v_mfma_f32_16x16x32_bf16 v[6:9], v[200:203], v[192:195], v[6:9]
	v_mfma_f32_16x16x32_bf16 v[2:5], v[208:211], v[192:195], v[2:5]
	v_mfma_f32_16x16x32_bf16 v[30:33], v[204:207], v[162:165], v[30:33]
	v_mfma_f32_16x16x32_bf16 v[26:29], v[212:215], v[162:165], v[26:29]
	v_mfma_f32_16x16x32_bf16 v[22:25], v[204:207], v[176:179], v[22:25]
	v_mfma_f32_16x16x32_bf16 v[18:21], v[212:215], v[176:179], v[18:21]
	v_mfma_f32_16x16x32_bf16 v[14:17], v[204:207], v[184:187], v[14:17]
	v_mfma_f32_16x16x32_bf16 v[10:13], v[212:215], v[184:187], v[10:13]
	v_mfma_f32_16x16x32_bf16 v[6:9], v[204:207], v[196:199], v[6:9]
	v_mfma_f32_16x16x32_bf16 v[2:5], v[212:215], v[196:199], v[2:5]
	s_add_i32 s10, 0, 0x18000
	v_add_u32_e32 v142, s10, v172
	s_barrier
	ds_read_b128 v[130:133], v142
	ds_read_b128 v[134:137], v142 offset:1024
	ds_read_b128 v[138:141], v142 offset:2048
	ds_read_b128 v[142:145], v142 offset:3072
	s_add_u32 s0, s48, 0x84000
	s_addc_u32 s1, s49, 0
	s_mov_b32 m0, s54
	ds_read_b128 v[158:161], v174 offset:32768
	ds_read_b128 v[162:165], v174 offset:33792
	ds_read_b128 v[166:169], v174 offset:34816
	ds_read_b128 v[176:179], v174 offset:35840
	ds_read_b128 v[180:183], v174 offset:36864
	ds_read_b128 v[184:187], v174 offset:37888
	ds_read_b128 v[192:195], v174 offset:38912
	ds_read_b128 v[196:199], v174 offset:39936
	global_load_lds_dwordx4 v146, s[0:1]
	s_mov_b32 m0, s55
	s_nop 0
	global_load_lds_dwordx4 v150, s[0:1]
	s_waitcnt lgkmcnt(8)
	s_barrier
	s_waitcnt lgkmcnt(0)
	s_waitcnt lgkmcnt(0)
	v_mfma_f32_16x16x32_bf16 v[126:129], v[130:133], v[158:161], v[126:129]
	v_mfma_f32_16x16x32_bf16 v[122:125], v[138:141], v[158:161], v[122:125]
	v_mfma_f32_16x16x32_bf16 v[118:121], v[130:133], v[166:169], v[118:121]
	v_mfma_f32_16x16x32_bf16 v[114:117], v[138:141], v[166:169], v[114:117]
	v_mfma_f32_16x16x32_bf16 v[110:113], v[130:133], v[180:183], v[110:113]
	v_mfma_f32_16x16x32_bf16 v[106:109], v[138:141], v[180:183], v[106:109]
	v_mfma_f32_16x16x32_bf16 v[102:105], v[130:133], v[192:195], v[102:105]
	v_mfma_f32_16x16x32_bf16 v[98:101], v[138:141], v[192:195], v[98:101]
	v_mfma_f32_16x16x32_bf16 v[126:129], v[134:137], v[162:165], v[126:129]
	v_mfma_f32_16x16x32_bf16 v[122:125], v[142:145], v[162:165], v[122:125]
	v_mfma_f32_16x16x32_bf16 v[118:121], v[134:137], v[176:179], v[118:121]
	v_mfma_f32_16x16x32_bf16 v[114:117], v[142:145], v[176:179], v[114:117]
	v_mfma_f32_16x16x32_bf16 v[110:113], v[134:137], v[184:187], v[110:113]
	v_mfma_f32_16x16x32_bf16 v[106:109], v[142:145], v[184:187], v[106:109]
	v_mfma_f32_16x16x32_bf16 v[102:105], v[134:137], v[196:199], v[102:105]
	v_mfma_f32_16x16x32_bf16 v[98:101], v[142:145], v[196:199], v[98:101]
	s_barrier
	s_add_i32 s11, 0, 0x1c000
	s_add_i32 s0, s10, s51
	v_add_u32_e32 v175, s11, v172
	s_add_u32 s98, s46, 0x80
	s_addc_u32 s99, s47, 0
	s_mov_b32 m0, s0
	ds_read_b128 v[200:203], v175
	ds_read_b128 v[204:207], v175 offset:1024
	ds_read_b128 v[208:211], v175 offset:2048
	ds_read_b128 v[212:215], v175 offset:3072
	global_load_lds_dwordx4 v148, s[98:99]
	s_add_i32 m0, s0, 0x2000
	s_nop 0
	global_load_lds_dwordx4 v152, s[98:99]
	s_barrier
; #define G_STAGE(bufoff, gbase, voff) do { _Pragma("unroll") for (int _i = 0; _i < 2; ++_i) \
;         __builtin_amdgcn_global_load_lds((const unsigned*)((const char*)(gbase) + (voff)[_i]), (LAS unsigned*)(lds + (bufoff) + ldsw + _i * 8192), 16, 0, 0); } while (0)
; #define G_WAIT_V(n) asm volatile("s_waitcnt vmcnt(" #n ")" ::: "memory")
; #define G_WAIT_L(n) asm volatile("s_waitcnt lgkmcnt(" #n ")" ::: "memory")
; #define G_BAR __builtin_amdgcn_s_barrier()
; #define G_SCHED __builtin_amdgcn_sched_barrier(0)
; template <int MODE  , class Epi, class Sched>
; __device__ __forceinline__ void gemm_phase(LAS unsigned char* lds, const GemmDesc g, const Sched& S, const Epi& E) {
;     ...
;             G_BAR; G_WAIT_L(0); G_MMA(0, 1, At, B1); G_BAR;
;             G_LDA(At, 1, 1); G_STAGE(G_SA(1, 0), a3, voffA);
;             G_BAR; G_WAIT_L(0); G_MMA(1, 0, At, B0); G_BAR; G_SCHED;
;             G_STAGE(G_SB(1, 1), b3 + hstepB, voffB);
;             G_WAIT_V(6); G_BAR; G_MMA(1, 1, At, B1); G_BAR;
;         }
	s_waitcnt lgkmcnt(0)
	s_waitcnt lgkmcnt(0)
	v_mfma_f32_16x16x32_bf16 v[94:97], v[200:203], v[158:161], v[94:97]
	v_mfma_f32_16x16x32_bf16 v[90:93], v[208:211], v[158:161], v[90:93]
	v_mfma_f32_16x16x32_bf16 v[86:89], v[200:203], v[166:169], v[86:89]
	v_mfma_f32_16x16x32_bf16 v[82:85], v[208:211], v[166:169], v[82:85]
	v_mfma_f32_16x16x32_bf16 v[78:81], v[200:203], v[180:183], v[78:81]
	v_mfma_f32_16x16x32_bf16 v[74:77], v[208:211], v[180:183], v[74:77]
	v_mfma_f32_16x16x32_bf16 v[70:73], v[200:203], v[192:195], v[70:73]
	v_mfma_f32_16x16x32_bf16 v[66:69], v[208:211], v[192:195], v[66:69]
	v_mfma_f32_16x16x32_bf16 v[94:97], v[204:207], v[162:165], v[94:97]
	v_mfma_f32_16x16x32_bf16 v[90:93], v[212:215], v[162:165], v[90:93]
	v_mfma_f32_16x16x32_bf16 v[86:89], v[204:207], v[176:179], v[86:89]
	v_mfma_f32_16x16x32_bf16 v[82:85], v[212:215], v[176:179], v[82:85]
	v_mfma_f32_16x16x32_bf16 v[78:81], v[204:207], v[184:187], v[78:81]
	v_mfma_f32_16x16x32_bf16 v[74:77], v[212:215], v[184:187], v[74:77]
	v_mfma_f32_16x16x32_bf16 v[70:73], v[204:207], v[196:199], v[70:73]
	v_mfma_f32_16x16x32_bf16 v[66:69], v[212:215], v[196:199], v[66:69]
	s_mov_b32 m0, s56
	s_add_u32 s98, s48, 0x80
	s_addc_u32 s99, s49, 0
	s_barrier
	ds_read_b128 v[158:161], v174 offset:49152
	ds_read_b128 v[162:165], v174 offset:50176
	ds_read_b128 v[166:169], v174 offset:51200
	ds_read_b128 v[176:179], v174 offset:52224
	ds_read_b128 v[180:183], v174 offset:53248
	ds_read_b128 v[184:187], v174 offset:54272
	ds_read_b128 v[192:195], v174 offset:55296
	ds_read_b128 v[196:199], v174 offset:56320
	global_load_lds_dwordx4 v146, s[98:99]
	s_mov_b32 m0, s57
	s_nop 0
	global_load_lds_dwordx4 v150, s[98:99]
	s_barrier
	s_waitcnt lgkmcnt(0)
	s_waitcnt lgkmcnt(0)
	v_mfma_f32_16x16x32_bf16 v[62:65], v[130:133], v[158:161], v[62:65]
	v_mfma_f32_16x16x32_bf16 v[58:61], v[138:141], v[158:161], v[58:61]
	v_mfma_f32_16x16x32_bf16 v[54:57], v[130:133], v[166:169], v[54:57]
	v_mfma_f32_16x16x32_bf16 v[50:53], v[138:141], v[166:169], v[50:53]
	v_mfma_f32_16x16x32_bf16 v[46:49], v[130:133], v[180:183], v[46:49]
	v_mfma_f32_16x16x32_bf16 v[42:45], v[138:141], v[180:183], v[42:45]
	v_mfma_f32_16x16x32_bf16 v[38:41], v[130:133], v[192:195], v[38:41]
	v_mfma_f32_16x16x32_bf16 v[34:37], v[138:141], v[192:195], v[34:37]
	v_mfma_f32_16x16x32_bf16 v[62:65], v[134:137], v[162:165], v[62:65]
	v_mfma_f32_16x16x32_bf16 v[58:61], v[142:145], v[162:165], v[58:61]
	v_mfma_f32_16x16x32_bf16 v[54:57], v[134:137], v[176:179], v[54:57]
	v_mfma_f32_16x16x32_bf16 v[50:53], v[142:145], v[176:179], v[50:53]
	v_mfma_f32_16x16x32_bf16 v[46:49], v[134:137], v[184:187], v[46:49]
	v_mfma_f32_16x16x32_bf16 v[42:45], v[142:145], v[184:187], v[42:45]
	v_mfma_f32_16x16x32_bf16 v[38:41], v[134:137], v[196:199], v[38:41]
	v_mfma_f32_16x16x32_bf16 v[34:37], v[142:145], v[196:199], v[34:37]
	s_barrier
	s_add_u32 s0, s46, 0x84080
	s_addc_u32 s1, s47, 0
	s_add_i32 s10, s11, s51
	s_mov_b32 m0, s10
	s_nop 0
	global_load_lds_dwordx4 v148, s[0:1]
	s_add_i32 m0, s10, 0x2000
	s_nop 0
	global_load_lds_dwordx4 v152, s[0:1]
	s_waitcnt vmcnt(6)
	s_barrier
	v_mfma_f32_16x16x32_bf16 v[30:33], v[200:203], v[158:161], v[30:33]
	s_add_i32 s68, s68, 2
	s_add_u32 s21, s21, 0x100
	s_addc_u32 s67, s67, 0
	s_cmp_gt_u32 s68, 13
	s_mov_b64 s[42:43], s[44:45]
	v_mfma_f32_16x16x32_bf16 v[26:29], v[208:211], v[158:161], v[26:29]
	v_mfma_f32_16x16x32_bf16 v[22:25], v[200:203], v[166:169], v[22:25]
	v_mfma_f32_16x16x32_bf16 v[18:21], v[208:211], v[166:169], v[18:21]
	v_mfma_f32_16x16x32_bf16 v[14:17], v[200:203], v[180:183], v[14:17]
	v_mfma_f32_16x16x32_bf16 v[10:13], v[208:211], v[180:183], v[10:13]
	v_mfma_f32_16x16x32_bf16 v[6:9], v[200:203], v[192:195], v[6:9]
	v_mfma_f32_16x16x32_bf16 v[2:5], v[208:211], v[192:195], v[2:5]
	v_mfma_f32_16x16x32_bf16 v[30:33], v[204:207], v[162:165], v[30:33]
	v_mfma_f32_16x16x32_bf16 v[26:29], v[212:215], v[162:165], v[26:29]
	v_mfma_f32_16x16x32_bf16 v[22:25], v[204:207], v[176:179], v[22:25]
	v_mfma_f32_16x16x32_bf16 v[18:21], v[212:215], v[176:179], v[18:21]
	v_mfma_f32_16x16x32_bf16 v[14:17], v[204:207], v[184:187], v[14:17]
	v_mfma_f32_16x16x32_bf16 v[10:13], v[212:215], v[184:187], v[10:13]
	v_mfma_f32_16x16x32_bf16 v[6:9], v[204:207], v[196:199], v[6:9]
	v_mfma_f32_16x16x32_bf16 v[2:5], v[212:215], v[196:199], v[2:5]
	s_cbranch_scc1 .Lkdone_sa
	s_barrier
	s_branch .LBB0_815

; #define G_STAGE(bufoff, gbase, voff) do { _Pragma("unroll") for (int _i = 0; _i < 2; ++_i) \
;         __builtin_amdgcn_global_load_lds((const unsigned*)((const char*)(gbase) + (voff)[_i]), (LAS unsigned*)(lds + (bufoff) + ldsw + _i * 8192), 16, 0, 0); } while (0)
; #define G_WAIT_V(n) asm volatile("s_waitcnt vmcnt(" #n ")" ::: "memory")
; #define G_WAIT_L(n) asm volatile("s_waitcnt lgkmcnt(" #n ")" ::: "memory")
; #define G_BAR __builtin_amdgcn_s_barrier()
; #define G_SCHED __builtin_amdgcn_sched_barrier(0)
; template <int MODE  , class Epi, class Sched>
; __device__ __forceinline__ void gemm_phase(LAS unsigned char* lds, const GemmDesc g, const Sched& S, const Epi& E) {
;     ...
;         for (int t = 0; t < nt; t += 2) {
;             const bool last = (t == nt - 2);
;             const char* a1 = cA + (size_t)(t + 1) * kstep;
;             const char* a2 = last ? nA : cA + (size_t)(t + 2) * kstep; const char* b2 = last ? nB : cB + (size_t)(t + 2) * kstep;
;             const char* a3 = a2 + kstep; const char* b3 = b2 + kstep;
;             G_LDB(B0, 0, 0); G_SCHED; G_LDA(At, 0, 0); G_STAGE(G_SA(1, 1), a1 + hstepA, voffA);
;             G_WAIT_L(8); G_BAR; G_WAIT_L(0); G_MMA(0, 0, At, B0); G_BAR; G_SCHED;
;             G_LDB(B1, 0, 1); G_STAGE(G_SB(0, 0), b2, voffB);
;             G_BAR; G_WAIT_L(0); G_MMA(0, 1, At, B1); G_BAR;
;             G_LDA(At, 0, 1); G_STAGE(G_SA(0, 0), a2, voffA);
;             G_BAR; G_WAIT_L(0); G_MMA(1, 0, At, B0); G_BAR; G_SCHED;
;             G_STAGE(G_SB(0, 1), b2 + hstepB, voffB);
;             G_WAIT_V(6); G_BAR; G_MMA(1, 1, At, B1); G_BAR;
.Lnodb_sb:
.LBB0_897:
	v_add_u32_e32 v142, s57, v174
	ds_read_b128 v[130:133], v142
	ds_read_b128 v[134:137], v142 offset:1024
	ds_read_b128 v[138:141], v142 offset:2048
	ds_read_b128 v[142:145], v142 offset:3072
	s_add_u32 s42, s40, 0x100
	s_addc_u32 s43, s41, 0
	s_cmp_eq_u32 s71, 12
	s_cselect_b32 s47, s21, s43
	s_cselect_b32 s46, s20, s42
	s_cselect_b32 s45, s3, s70
	s_cselect_b32 s44, s2, s19
	s_add_u32 s98, s40, 0x84080
	s_addc_u32 s99, s41, 0
	s_add_i32 m0, s50, 0xc000
	ds_read_b128 v[158:161], v176
	ds_read_b128 v[162:165], v176 offset:1024
	ds_read_b128 v[166:169], v176 offset:2048
	ds_read_b128 v[170:173], v176 offset:3072
	ds_read_b128 v[178:181], v176 offset:4096
	ds_read_b128 v[182:185], v176 offset:5120
	ds_read_b128 v[186:189], v176 offset:6144
	ds_read_b128 v[192:195], v176 offset:7168
	global_load_lds_dwordx4 v146, s[98:99]
	s_add_i32 m0, s50, 0xe000
	s_nop 0
	global_load_lds_dwordx4 v150, s[98:99]
	s_waitcnt lgkmcnt(8)
	s_barrier
	s_waitcnt lgkmcnt(0)
	s_waitcnt lgkmcnt(0)
	v_mfma_f32_16x16x32_bf16 v[126:129], v[130:133], v[158:161], v[126:129]
	v_mfma_f32_16x16x32_bf16 v[122:125], v[138:141], v[158:161], v[122:125]
	v_mfma_f32_16x16x32_bf16 v[118:121], v[130:133], v[166:169], v[118:121]
	v_mfma_f32_16x16x32_bf16 v[114:117], v[138:141], v[166:169], v[114:117]
	v_mfma_f32_16x16x32_bf16 v[110:113], v[130:133], v[178:181], v[110:113]
	v_mfma_f32_16x16x32_bf16 v[106:109], v[138:141], v[178:181], v[106:109]
	v_mfma_f32_16x16x32_bf16 v[102:105], v[130:133], v[186:189], v[102:105]
	v_mfma_f32_16x16x32_bf16 v[98:101], v[138:141], v[186:189], v[98:101]
	v_mfma_f32_16x16x32_bf16 v[126:129], v[134:137], v[162:165], v[126:129]
	v_mfma_f32_16x16x32_bf16 v[122:125], v[142:145], v[162:165], v[122:125]
	v_mfma_f32_16x16x32_bf16 v[118:121], v[134:137], v[170:173], v[118:121]
	v_mfma_f32_16x16x32_bf16 v[114:117], v[142:145], v[170:173], v[114:117]
	v_mfma_f32_16x16x32_bf16 v[110:113], v[134:137], v[182:185], v[110:113]
	v_mfma_f32_16x16x32_bf16 v[106:109], v[142:145], v[182:185], v[106:109]
	v_mfma_f32_16x16x32_bf16 v[102:105], v[134:137], v[192:195], v[102:105]
	v_mfma_f32_16x16x32_bf16 v[98:101], v[142:145], v[192:195], v[98:101]
	s_barrier
	s_add_i32 s0, s57, s49
	v_add_u32_e32 v177, s58, v174
	s_mov_b32 m0, s0
	ds_read_b128 v[196:199], v177
	ds_read_b128 v[200:203], v177 offset:1024
	ds_read_b128 v[204:207], v177 offset:2048
	ds_read_b128 v[208:211], v177 offset:3072
	global_load_lds_dwordx4 v148, s[44:45]
	s_add_i32 m0, s0, 0x2000
	s_nop 0
	global_load_lds_dwordx4 v152, s[44:45]
	s_barrier
	s_waitcnt lgkmcnt(0)
	s_waitcnt lgkmcnt(0)
	v_mfma_f32_16x16x32_bf16 v[94:97], v[196:199], v[158:161], v[94:97]
	v_mfma_f32_16x16x32_bf16 v[90:93], v[204:207], v[158:161], v[90:93]
	v_mfma_f32_16x16x32_bf16 v[86:89], v[196:199], v[166:169], v[86:89]
	v_mfma_f32_16x16x32_bf16 v[82:85], v[204:207], v[166:169], v[82:85]
	v_mfma_f32_16x16x32_bf16 v[78:81], v[196:199], v[178:181], v[78:81]
	v_mfma_f32_16x16x32_bf16 v[74:77], v[204:207], v[178:181], v[74:77]
	v_mfma_f32_16x16x32_bf16 v[70:73], v[196:199], v[186:189], v[70:73]
	v_mfma_f32_16x16x32_bf16 v[66:69], v[204:207], v[186:189], v[66:69]
	v_mfma_f32_16x16x32_bf16 v[94:97], v[200:203], v[162:165], v[94:97]
	v_mfma_f32_16x16x32_bf16 v[90:93], v[208:211], v[162:165], v[90:93]
	v_mfma_f32_16x16x32_bf16 v[86:89], v[200:203], v[170:173], v[86:89]
	v_mfma_f32_16x16x32_bf16 v[82:85], v[208:211], v[170:173], v[82:85]
	v_mfma_f32_16x16x32_bf16 v[78:81], v[200:203], v[182:185], v[78:81]
	v_mfma_f32_16x16x32_bf16 v[74:77], v[208:211], v[182:185], v[74:77]
	v_mfma_f32_16x16x32_bf16 v[70:73], v[200:203], v[192:195], v[70:73]
	v_mfma_f32_16x16x32_bf16 v[66:69], v[208:211], v[192:195], v[66:69]
	s_mov_b32 m0, s50
	s_barrier
	ds_read_b128 v[158:161], v176 offset:16384
	ds_read_b128 v[162:165], v176 offset:17408
	ds_read_b128 v[166:169], v176 offset:18432
	ds_read_b128 v[170:173], v176 offset:19456
	ds_read_b128 v[178:181], v176 offset:20480
	ds_read_b128 v[182:185], v176 offset:21504
	ds_read_b128 v[186:189], v176 offset:22528
	ds_read_b128 v[192:195], v176 offset:23552
	global_load_lds_dwordx4 v146, s[46:47]
	s_mov_b32 m0, s51
	s_nop 0
	global_load_lds_dwordx4 v150, s[46:47]
	s_barrier
	s_waitcnt lgkmcnt(0)
	s_waitcnt lgkmcnt(0)
	v_mfma_f32_16x16x32_bf16 v[62:65], v[130:133], v[158:161], v[62:65]
	v_mfma_f32_16x16x32_bf16 v[58:61], v[138:141], v[158:161], v[58:61]
	v_mfma_f32_16x16x32_bf16 v[54:57], v[130:133], v[166:169], v[54:57]
	v_mfma_f32_16x16x32_bf16 v[50:53], v[138:141], v[166:169], v[50:53]
	v_mfma_f32_16x16x32_bf16 v[46:49], v[130:133], v[178:181], v[46:49]
	v_mfma_f32_16x16x32_bf16 v[42:45], v[138:141], v[178:181], v[42:45]
	v_mfma_f32_16x16x32_bf16 v[38:41], v[130:133], v[186:189], v[38:41]
	v_mfma_f32_16x16x32_bf16 v[34:37], v[138:141], v[186:189], v[34:37]
	v_mfma_f32_16x16x32_bf16 v[62:65], v[134:137], v[162:165], v[62:65]
	v_mfma_f32_16x16x32_bf16 v[58:61], v[142:145], v[162:165], v[58:61]
	v_mfma_f32_16x16x32_bf16 v[54:57], v[134:137], v[170:173], v[54:57]
	v_mfma_f32_16x16x32_bf16 v[50:53], v[142:145], v[170:173], v[50:53]
	v_mfma_f32_16x16x32_bf16 v[46:49], v[134:137], v[182:185], v[46:49]
	v_mfma_f32_16x16x32_bf16 v[42:45], v[142:145], v[182:185], v[42:45]
	v_mfma_f32_16x16x32_bf16 v[38:41], v[134:137], v[192:195], v[38:41]
	v_mfma_f32_16x16x32_bf16 v[34:37], v[142:145], v[192:195], v[34:37]
	s_barrier
	s_add_u32 s0, s44, 0x84000
	s_addc_u32 s1, s45, 0
	s_add_i32 s10, s58, s49
	s_mov_b32 m0, s10
	s_nop 0
	global_load_lds_dwordx4 v148, s[0:1]
	s_add_i32 m0, s10, 0x2000
	s_nop 0
	global_load_lds_dwordx4 v152, s[0:1]
	s_waitcnt vmcnt(6)
	s_barrier
; #define G_STAGE(bufoff, gbase, voff) do { _Pragma("unroll") for (int _i = 0; _i < 2; ++_i) \
;         __builtin_amdgcn_global_load_lds((const unsigned*)((const char*)(gbase) + (voff)[_i]), (LAS unsigned*)(lds + (bufoff) + ldsw + _i * 8192), 16, 0, 0); } while (0)
; #define G_WAIT_V(n) asm volatile("s_waitcnt vmcnt(" #n ")" ::: "memory")
; #define G_WAIT_L(n) asm volatile("s_waitcnt lgkmcnt(" #n ")" ::: "memory")
; #define G_BAR __builtin_amdgcn_s_barrier()
; #define G_SCHED __builtin_amdgcn_sched_barrier(0)
; template <int MODE  , class Epi, class Sched>
; __device__ __forceinline__ void gemm_phase(LAS unsigned char* lds, const GemmDesc g, const Sched& S, const Epi& E) {
;     ...
;             G_WAIT_V(6); G_BAR; G_MMA(1, 1, At, B1); G_BAR;
;             G_LDB(B0, 1, 0); G_SCHED; G_LDA(At, 1, 0); G_STAGE(G_SA(0, 1), a2 + hstepA, voffA);
;             G_WAIT_L(8); G_BAR; G_WAIT_L(0); G_MMA(0, 0, At, B0); G_BAR; G_SCHED;
;             G_LDB(B1, 1, 1); G_STAGE(G_SB(1, 0), b3, voffB);
;             G_BAR; G_WAIT_L(0); G_MMA(0, 1, At, B1); G_BAR;
;             G_LDA(At, 1, 1); G_STAGE(G_SA(1, 0), a3, voffA);
	v_mfma_f32_16x16x32_bf16 v[30:33], v[196:199], v[158:161], v[30:33]
	v_mfma_f32_16x16x32_bf16 v[26:29], v[204:207], v[158:161], v[26:29]
	v_mfma_f32_16x16x32_bf16 v[22:25], v[196:199], v[166:169], v[22:25]
	v_mfma_f32_16x16x32_bf16 v[18:21], v[204:207], v[166:169], v[18:21]
	v_mfma_f32_16x16x32_bf16 v[14:17], v[196:199], v[178:181], v[14:17]
	v_mfma_f32_16x16x32_bf16 v[10:13], v[204:207], v[178:181], v[10:13]
	v_mfma_f32_16x16x32_bf16 v[6:9], v[196:199], v[186:189], v[6:9]
	v_mfma_f32_16x16x32_bf16 v[2:5], v[204:207], v[186:189], v[2:5]
	v_mfma_f32_16x16x32_bf16 v[30:33], v[200:203], v[162:165], v[30:33]
	v_mfma_f32_16x16x32_bf16 v[26:29], v[208:211], v[162:165], v[26:29]
	v_mfma_f32_16x16x32_bf16 v[22:25], v[200:203], v[170:173], v[22:25]
	v_mfma_f32_16x16x32_bf16 v[18:21], v[208:211], v[170:173], v[18:21]
	v_mfma_f32_16x16x32_bf16 v[14:17], v[200:203], v[182:185], v[14:17]
	v_mfma_f32_16x16x32_bf16 v[10:13], v[208:211], v[182:185], v[10:13]
	v_mfma_f32_16x16x32_bf16 v[6:9], v[200:203], v[192:195], v[6:9]
	v_mfma_f32_16x16x32_bf16 v[2:5], v[208:211], v[192:195], v[2:5]
	s_add_i32 s10, 0, 0x18000
	v_add_u32_e32 v142, s10, v174
	s_barrier
	ds_read_b128 v[130:133], v142
	ds_read_b128 v[134:137], v142 offset:1024
	ds_read_b128 v[138:141], v142 offset:2048
	ds_read_b128 v[142:145], v142 offset:3072
	s_add_u32 s0, s46, 0x84000
	s_addc_u32 s1, s47, 0
	s_mov_b32 m0, s52
	ds_read_b128 v[158:161], v176 offset:32768
	ds_read_b128 v[162:165], v176 offset:33792
	ds_read_b128 v[166:169], v176 offset:34816
	ds_read_b128 v[170:173], v176 offset:35840
	ds_read_b128 v[178:181], v176 offset:36864
	ds_read_b128 v[182:185], v176 offset:37888
	ds_read_b128 v[186:189], v176 offset:38912
	ds_read_b128 v[192:195], v176 offset:39936
	global_load_lds_dwordx4 v146, s[0:1]
	s_mov_b32 m0, s53
	s_nop 0
	global_load_lds_dwordx4 v150, s[0:1]
	s_waitcnt lgkmcnt(8)
	s_barrier
	s_waitcnt lgkmcnt(0)
	s_waitcnt lgkmcnt(0)
	v_mfma_f32_16x16x32_bf16 v[126:129], v[130:133], v[158:161], v[126:129]
	v_mfma_f32_16x16x32_bf16 v[122:125], v[138:141], v[158:161], v[122:125]
	v_mfma_f32_16x16x32_bf16 v[118:121], v[130:133], v[166:169], v[118:121]
	v_mfma_f32_16x16x32_bf16 v[114:117], v[138:141], v[166:169], v[114:117]
	v_mfma_f32_16x16x32_bf16 v[110:113], v[130:133], v[178:181], v[110:113]
	v_mfma_f32_16x16x32_bf16 v[106:109], v[138:141], v[178:181], v[106:109]
	v_mfma_f32_16x16x32_bf16 v[102:105], v[130:133], v[186:189], v[102:105]
	v_mfma_f32_16x16x32_bf16 v[98:101], v[138:141], v[186:189], v[98:101]
	v_mfma_f32_16x16x32_bf16 v[126:129], v[134:137], v[162:165], v[126:129]
	v_mfma_f32_16x16x32_bf16 v[122:125], v[142:145], v[162:165], v[122:125]
	v_mfma_f32_16x16x32_bf16 v[118:121], v[134:137], v[170:173], v[118:121]
	v_mfma_f32_16x16x32_bf16 v[114:117], v[142:145], v[170:173], v[114:117]
	v_mfma_f32_16x16x32_bf16 v[110:113], v[134:137], v[182:185], v[110:113]
	v_mfma_f32_16x16x32_bf16 v[106:109], v[142:145], v[182:185], v[106:109]
	v_mfma_f32_16x16x32_bf16 v[102:105], v[134:137], v[192:195], v[102:105]
	v_mfma_f32_16x16x32_bf16 v[98:101], v[142:145], v[192:195], v[98:101]
	s_barrier
	s_add_i32 s11, 0, 0x1c000
	s_add_i32 s0, s10, s49
	v_add_u32_e32 v177, s11, v174
	s_add_u32 s98, s44, 0x80
	s_addc_u32 s99, s45, 0
	s_mov_b32 m0, s0
	ds_read_b128 v[196:199], v177
	ds_read_b128 v[200:203], v177 offset:1024
	ds_read_b128 v[204:207], v177 offset:2048
	ds_read_b128 v[208:211], v177 offset:3072
	global_load_lds_dwordx4 v148, s[98:99]
	s_add_i32 m0, s0, 0x2000
	s_nop 0
	global_load_lds_dwordx4 v152, s[98:99]
	s_barrier
; #define G_STAGE(bufoff, gbase, voff) do { _Pragma("unroll") for (int _i = 0; _i < 2; ++_i) \
;         __builtin_amdgcn_global_load_lds((const unsigned*)((const char*)(gbase) + (voff)[_i]), (LAS unsigned*)(lds + (bufoff) + ldsw + _i * 8192), 16, 0, 0); } while (0)
; #define G_WAIT_V(n) asm volatile("s_waitcnt vmcnt(" #n ")" ::: "memory")
; #define G_WAIT_L(n) asm volatile("s_waitcnt lgkmcnt(" #n ")" ::: "memory")
; #define G_BAR __builtin_amdgcn_s_barrier()
; #define G_SCHED __builtin_amdgcn_sched_barrier(0)
; template <int MODE  , class Epi, class Sched>
; __device__ __forceinline__ void gemm_phase(LAS unsigned char* lds, const GemmDesc g, const Sched& S, const Epi& E) {
;     ...
;             G_LDA(At, 1, 1); G_STAGE(G_SA(1, 0), a3, voffA);
;             G_BAR; G_WAIT_L(0); G_MMA(1, 0, At, B0); G_BAR; G_SCHED;
;             G_STAGE(G_SB(1, 1), b3 + hstepB, voffB);
;             G_WAIT_V(6); G_BAR; G_MMA(1, 1, At, B1); G_BAR;
;         }
	s_waitcnt lgkmcnt(0)
	s_waitcnt lgkmcnt(0)
	v_mfma_f32_16x16x32_bf16 v[94:97], v[196:199], v[158:161], v[94:97]
	v_mfma_f32_16x16x32_bf16 v[90:93], v[204:207], v[158:161], v[90:93]
	v_mfma_f32_16x16x32_bf16 v[86:89], v[196:199], v[166:169], v[86:89]
	v_mfma_f32_16x16x32_bf16 v[82:85], v[204:207], v[166:169], v[82:85]
	v_mfma_f32_16x16x32_bf16 v[78:81], v[196:199], v[178:181], v[78:81]
	v_mfma_f32_16x16x32_bf16 v[74:77], v[204:207], v[178:181], v[74:77]
	v_mfma_f32_16x16x32_bf16 v[70:73], v[196:199], v[186:189], v[70:73]
	v_mfma_f32_16x16x32_bf16 v[66:69], v[204:207], v[186:189], v[66:69]
	v_mfma_f32_16x16x32_bf16 v[94:97], v[200:203], v[162:165], v[94:97]
	v_mfma_f32_16x16x32_bf16 v[90:93], v[208:211], v[162:165], v[90:93]
	v_mfma_f32_16x16x32_bf16 v[86:89], v[200:203], v[170:173], v[86:89]
	v_mfma_f32_16x16x32_bf16 v[82:85], v[208:211], v[170:173], v[82:85]
	v_mfma_f32_16x16x32_bf16 v[78:81], v[200:203], v[182:185], v[78:81]
	v_mfma_f32_16x16x32_bf16 v[74:77], v[208:211], v[182:185], v[74:77]
	v_mfma_f32_16x16x32_bf16 v[70:73], v[200:203], v[192:195], v[70:73]
	v_mfma_f32_16x16x32_bf16 v[66:69], v[208:211], v[192:195], v[66:69]
	s_mov_b32 m0, s54
	s_add_u32 s98, s46, 0x80
	s_addc_u32 s99, s47, 0
	s_barrier
	ds_read_b128 v[158:161], v176 offset:49152
	ds_read_b128 v[162:165], v176 offset:50176
	ds_read_b128 v[166:169], v176 offset:51200
	ds_read_b128 v[170:173], v176 offset:52224
	ds_read_b128 v[178:181], v176 offset:53248
	ds_read_b128 v[182:185], v176 offset:54272
	ds_read_b128 v[186:189], v176 offset:55296
	ds_read_b128 v[192:195], v176 offset:56320
	global_load_lds_dwordx4 v146, s[98:99]
	s_mov_b32 m0, s55
	s_nop 0
	global_load_lds_dwordx4 v150, s[98:99]
	s_barrier
	s_waitcnt lgkmcnt(0)
	s_waitcnt lgkmcnt(0)
	v_mfma_f32_16x16x32_bf16 v[62:65], v[130:133], v[158:161], v[62:65]
	v_mfma_f32_16x16x32_bf16 v[58:61], v[138:141], v[158:161], v[58:61]
	v_mfma_f32_16x16x32_bf16 v[54:57], v[130:133], v[166:169], v[54:57]
	v_mfma_f32_16x16x32_bf16 v[50:53], v[138:141], v[166:169], v[50:53]
	v_mfma_f32_16x16x32_bf16 v[46:49], v[130:133], v[178:181], v[46:49]
	v_mfma_f32_16x16x32_bf16 v[42:45], v[138:141], v[178:181], v[42:45]
	v_mfma_f32_16x16x32_bf16 v[38:41], v[130:133], v[186:189], v[38:41]
	v_mfma_f32_16x16x32_bf16 v[34:37], v[138:141], v[186:189], v[34:37]
	v_mfma_f32_16x16x32_bf16 v[62:65], v[134:137], v[162:165], v[62:65]
	v_mfma_f32_16x16x32_bf16 v[58:61], v[142:145], v[162:165], v[58:61]
	v_mfma_f32_16x16x32_bf16 v[54:57], v[134:137], v[170:173], v[54:57]
	v_mfma_f32_16x16x32_bf16 v[50:53], v[142:145], v[170:173], v[50:53]
	v_mfma_f32_16x16x32_bf16 v[46:49], v[134:137], v[182:185], v[46:49]
	v_mfma_f32_16x16x32_bf16 v[42:45], v[142:145], v[182:185], v[42:45]
	v_mfma_f32_16x16x32_bf16 v[38:41], v[134:137], v[192:195], v[38:41]
	v_mfma_f32_16x16x32_bf16 v[34:37], v[142:145], v[192:195], v[34:37]
	s_barrier
	s_add_u32 s0, s44, 0x84080
	s_addc_u32 s1, s45, 0
	s_add_i32 s10, s11, s49
	s_mov_b32 m0, s10
	s_nop 0
	global_load_lds_dwordx4 v148, s[0:1]
	s_add_i32 m0, s10, 0x2000
	s_nop 0
	global_load_lds_dwordx4 v152, s[0:1]
	s_waitcnt vmcnt(6)
	s_barrier
	v_mfma_f32_16x16x32_bf16 v[30:33], v[196:199], v[158:161], v[30:33]
	s_add_i32 s71, s71, 2
	s_add_u32 s19, s19, 0x100
	s_addc_u32 s70, s70, 0
	s_cmp_gt_u32 s71, 13
	s_mov_b64 s[40:41], s[42:43]
	v_mfma_f32_16x16x32_bf16 v[26:29], v[204:207], v[158:161], v[26:29]
	v_mfma_f32_16x16x32_bf16 v[22:25], v[196:199], v[166:169], v[22:25]
	v_mfma_f32_16x16x32_bf16 v[18:21], v[204:207], v[166:169], v[18:21]
	v_mfma_f32_16x16x32_bf16 v[14:17], v[196:199], v[178:181], v[14:17]
	v_mfma_f32_16x16x32_bf16 v[10:13], v[204:207], v[178:181], v[10:13]
	v_mfma_f32_16x16x32_bf16 v[6:9], v[196:199], v[186:189], v[6:9]
	v_mfma_f32_16x16x32_bf16 v[2:5], v[204:207], v[186:189], v[2:5]
	v_mfma_f32_16x16x32_bf16 v[30:33], v[200:203], v[162:165], v[30:33]
	v_mfma_f32_16x16x32_bf16 v[26:29], v[208:211], v[162:165], v[26:29]
	v_mfma_f32_16x16x32_bf16 v[22:25], v[200:203], v[170:173], v[22:25]
	v_mfma_f32_16x16x32_bf16 v[18:21], v[208:211], v[170:173], v[18:21]
	v_mfma_f32_16x16x32_bf16 v[14:17], v[200:203], v[182:185], v[14:17]
	v_mfma_f32_16x16x32_bf16 v[10:13], v[208:211], v[182:185], v[10:13]
	v_mfma_f32_16x16x32_bf16 v[6:9], v[200:203], v[192:195], v[6:9]
	v_mfma_f32_16x16x32_bf16 v[2:5], v[208:211], v[192:195], v[2:5]
	s_cbranch_scc1 .Lkdone_sb
	s_barrier
	s_branch .LBB0_897

; #define G_STAGE(bufoff, gbase, voff) do { _Pragma("unroll") for (int _i = 0; _i < 2; ++_i) \
;         __builtin_amdgcn_global_load_lds((const unsigned*)((const char*)(gbase) + (voff)[_i]), (LAS unsigned*)(lds + (bufoff) + ldsw + _i * 8192), 16, 0, 0); } while (0)
; #define G_WAIT_V(n) asm volatile("s_waitcnt vmcnt(" #n ")" ::: "memory")
; #define G_WAIT_L(n) asm volatile("s_waitcnt lgkmcnt(" #n ")" ::: "memory")
; #define G_BAR __builtin_amdgcn_s_barrier()
; #define G_SCHED __builtin_amdgcn_sched_barrier(0)
; template <int MODE  , class Epi, class Sched>
; __device__ __forceinline__ void gemm_phase(LAS unsigned char* lds, const GemmDesc g, const Sched& S, const Epi& E) {
;     ...
;         for (int t = 0; t < nt; t += 2) {
;             const bool last = (t == nt - 2);
;             const char* a1 = cA + (size_t)(t + 1) * kstep;
;             const char* a2 = last ? nA : cA + (size_t)(t + 2) * kstep; const char* b2 = last ? nB : cB + (size_t)(t + 2) * kstep;
;             const char* a3 = a2 + kstep; const char* b3 = b2 + kstep;
;             G_LDB(B0, 0, 0); G_SCHED; G_LDA(At, 0, 0); G_STAGE(G_SA(1, 1), a1 + hstepA, voffA);
;             G_WAIT_L(8); G_BAR; G_WAIT_L(0); G_MMA(0, 0, At, B0); G_BAR; G_SCHED;
;             G_LDB(B1, 0, 1); G_STAGE(G_SB(0, 0), b2, voffB);
;             G_BAR; G_WAIT_L(0); G_MMA(0, 1, At, B1); G_BAR;
;             G_LDA(At, 0, 1); G_STAGE(G_SA(0, 0), a2, voffA);
;             G_BAR; G_WAIT_L(0); G_MMA(1, 0, At, B0); G_BAR; G_SCHED;
;             G_STAGE(G_SB(0, 1), b2 + hstepB, voffB);
;             G_WAIT_V(6); G_BAR; G_MMA(1, 1, At, B1); G_BAR;
.Lnodb_sc:
.LBB0_987:
	v_add_u32_e32 v145, s50, v142
	ds_read_b128 v[146:149], v145
	ds_read_b128 v[150:153], v145 offset:1024
	ds_read_b128 v[154:157], v145 offset:2048
	ds_read_b128 v[158:161], v145 offset:3072
	s_add_u32 s34, s20, 0x100
	s_addc_u32 s35, s21, 0
	s_cmp_eq_u32 s60, 12
	s_cselect_b32 s43, s17, s35
	s_cselect_b32 s42, s16, s34
	s_cselect_b32 s41, s3, s59
	s_cselect_b32 s40, s2, s15
	s_add_u32 s98, s20, 0x84080
	s_addc_u32 s99, s21, 0
	s_add_i32 m0, s44, 0xc000
	ds_read_b128 v[162:165], v144
	ds_read_b128 v[166:169], v144 offset:1024
	ds_read_b128 v[170:173], v144 offset:2048
	ds_read_b128 v[174:177], v144 offset:3072
	ds_read_b128 v[178:181], v144 offset:4096
	ds_read_b128 v[182:185], v144 offset:5120
	ds_read_b128 v[186:189], v144 offset:6144
	ds_read_b128 v[192:195], v144 offset:7168
	global_load_lds_dwordx4 v130, s[98:99]
	s_add_i32 m0, s44, 0xe000
	s_nop 0
	global_load_lds_dwordx4 v134, s[98:99]
	s_waitcnt lgkmcnt(8)
	s_barrier
	s_waitcnt lgkmcnt(0)
	s_waitcnt lgkmcnt(0)
	v_mfma_f32_16x16x32_bf16 v[126:129], v[146:149], v[162:165], v[126:129]
	v_mfma_f32_16x16x32_bf16 v[122:125], v[154:157], v[162:165], v[122:125]
	v_mfma_f32_16x16x32_bf16 v[118:121], v[146:149], v[170:173], v[118:121]
	v_mfma_f32_16x16x32_bf16 v[114:117], v[154:157], v[170:173], v[114:117]
	v_mfma_f32_16x16x32_bf16 v[110:113], v[146:149], v[178:181], v[110:113]
	v_mfma_f32_16x16x32_bf16 v[106:109], v[154:157], v[178:181], v[106:109]
	v_mfma_f32_16x16x32_bf16 v[102:105], v[146:149], v[186:189], v[102:105]
	v_mfma_f32_16x16x32_bf16 v[98:101], v[154:157], v[186:189], v[98:101]
	v_mfma_f32_16x16x32_bf16 v[126:129], v[150:153], v[166:169], v[126:129]
	v_mfma_f32_16x16x32_bf16 v[122:125], v[158:161], v[166:169], v[122:125]
	v_mfma_f32_16x16x32_bf16 v[118:121], v[150:153], v[174:177], v[118:121]
	v_mfma_f32_16x16x32_bf16 v[114:117], v[158:161], v[174:177], v[114:117]
	v_mfma_f32_16x16x32_bf16 v[110:113], v[150:153], v[182:185], v[110:113]
	v_mfma_f32_16x16x32_bf16 v[106:109], v[158:161], v[182:185], v[106:109]
	v_mfma_f32_16x16x32_bf16 v[102:105], v[150:153], v[192:195], v[102:105]
	v_mfma_f32_16x16x32_bf16 v[98:101], v[158:161], v[192:195], v[98:101]
	s_barrier
	s_add_i32 s0, s50, s31
	v_add_u32_e32 v145, s51, v142
	s_mov_b32 m0, s0
	ds_read_b128 v[196:199], v145
	ds_read_b128 v[200:203], v145 offset:1024
	ds_read_b128 v[204:207], v145 offset:2048
	ds_read_b128 v[208:211], v145 offset:3072
	global_load_lds_dwordx4 v132, s[40:41]
	s_add_i32 m0, s0, 0x2000
	s_nop 0
	global_load_lds_dwordx4 v136, s[40:41]
	s_barrier
	s_waitcnt lgkmcnt(0)
	s_waitcnt lgkmcnt(0)
	v_mfma_f32_16x16x32_bf16 v[94:97], v[196:199], v[162:165], v[94:97]
	v_mfma_f32_16x16x32_bf16 v[90:93], v[204:207], v[162:165], v[90:93]
	v_mfma_f32_16x16x32_bf16 v[86:89], v[196:199], v[170:173], v[86:89]
	v_mfma_f32_16x16x32_bf16 v[82:85], v[204:207], v[170:173], v[82:85]
	v_mfma_f32_16x16x32_bf16 v[78:81], v[196:199], v[178:181], v[78:81]
	v_mfma_f32_16x16x32_bf16 v[74:77], v[204:207], v[178:181], v[74:77]
	v_mfma_f32_16x16x32_bf16 v[70:73], v[196:199], v[186:189], v[70:73]
	v_mfma_f32_16x16x32_bf16 v[66:69], v[204:207], v[186:189], v[66:69]
	v_mfma_f32_16x16x32_bf16 v[94:97], v[200:203], v[166:169], v[94:97]
	v_mfma_f32_16x16x32_bf16 v[90:93], v[208:211], v[166:169], v[90:93]
	v_mfma_f32_16x16x32_bf16 v[86:89], v[200:203], v[174:177], v[86:89]
	v_mfma_f32_16x16x32_bf16 v[82:85], v[208:211], v[174:177], v[82:85]
	v_mfma_f32_16x16x32_bf16 v[78:81], v[200:203], v[182:185], v[78:81]
	v_mfma_f32_16x16x32_bf16 v[74:77], v[208:211], v[182:185], v[74:77]
	v_mfma_f32_16x16x32_bf16 v[70:73], v[200:203], v[192:195], v[70:73]
	v_mfma_f32_16x16x32_bf16 v[66:69], v[208:211], v[192:195], v[66:69]
	s_mov_b32 m0, s44
	s_barrier
	ds_read_b128 v[162:165], v144 offset:16384
	ds_read_b128 v[166:169], v144 offset:17408
	ds_read_b128 v[170:173], v144 offset:18432
	ds_read_b128 v[174:177], v144 offset:19456
	ds_read_b128 v[178:181], v144 offset:20480
	ds_read_b128 v[182:185], v144 offset:21504
	ds_read_b128 v[186:189], v144 offset:22528
	ds_read_b128 v[192:195], v144 offset:23552
	global_load_lds_dwordx4 v130, s[42:43]
	s_mov_b32 m0, s45
	s_nop 0
	global_load_lds_dwordx4 v134, s[42:43]
	s_barrier
	s_waitcnt lgkmcnt(0)
	s_waitcnt lgkmcnt(0)
	v_mfma_f32_16x16x32_bf16 v[62:65], v[146:149], v[162:165], v[62:65]
	v_mfma_f32_16x16x32_bf16 v[58:61], v[154:157], v[162:165], v[58:61]
	v_mfma_f32_16x16x32_bf16 v[54:57], v[146:149], v[170:173], v[54:57]
	v_mfma_f32_16x16x32_bf16 v[50:53], v[154:157], v[170:173], v[50:53]
	v_mfma_f32_16x16x32_bf16 v[46:49], v[146:149], v[178:181], v[46:49]
	v_mfma_f32_16x16x32_bf16 v[42:45], v[154:157], v[178:181], v[42:45]
	v_mfma_f32_16x16x32_bf16 v[38:41], v[146:149], v[186:189], v[38:41]
	v_mfma_f32_16x16x32_bf16 v[34:37], v[154:157], v[186:189], v[34:37]
	v_mfma_f32_16x16x32_bf16 v[62:65], v[150:153], v[166:169], v[62:65]
	v_mfma_f32_16x16x32_bf16 v[58:61], v[158:161], v[166:169], v[58:61]
	v_mfma_f32_16x16x32_bf16 v[54:57], v[150:153], v[174:177], v[54:57]
	v_mfma_f32_16x16x32_bf16 v[50:53], v[158:161], v[174:177], v[50:53]
	v_mfma_f32_16x16x32_bf16 v[46:49], v[150:153], v[182:185], v[46:49]
	v_mfma_f32_16x16x32_bf16 v[42:45], v[158:161], v[182:185], v[42:45]
	v_mfma_f32_16x16x32_bf16 v[38:41], v[150:153], v[192:195], v[38:41]
	v_mfma_f32_16x16x32_bf16 v[34:37], v[158:161], v[192:195], v[34:37]
	s_barrier
	s_add_u32 s0, s40, 0x84000
	s_addc_u32 s1, s41, 0
	s_add_i32 s10, s51, s31
	s_mov_b32 m0, s10
	s_nop 0
	global_load_lds_dwordx4 v132, s[0:1]
	s_add_i32 m0, s10, 0x2000
	s_nop 0
	global_load_lds_dwordx4 v136, s[0:1]
	s_waitcnt vmcnt(6)
	s_barrier
; #define G_STAGE(bufoff, gbase, voff) do { _Pragma("unroll") for (int _i = 0; _i < 2; ++_i) \
;         __builtin_amdgcn_global_load_lds((const unsigned*)((const char*)(gbase) + (voff)[_i]), (LAS unsigned*)(lds + (bufoff) + ldsw + _i * 8192), 16, 0, 0); } while (0)
; #define G_WAIT_V(n) asm volatile("s_waitcnt vmcnt(" #n ")" ::: "memory")
; #define G_WAIT_L(n) asm volatile("s_waitcnt lgkmcnt(" #n ")" ::: "memory")
; #define G_BAR __builtin_amdgcn_s_barrier()
; #define G_SCHED __builtin_amdgcn_sched_barrier(0)
; template <int MODE  , class Epi, class Sched>
; __device__ __forceinline__ void gemm_phase(LAS unsigned char* lds, const GemmDesc g, const Sched& S, const Epi& E) {
;     ...
;             G_WAIT_V(6); G_BAR; G_MMA(1, 1, At, B1); G_BAR;
;             G_LDB(B0, 1, 0); G_SCHED; G_LDA(At, 1, 0); G_STAGE(G_SA(0, 1), a2 + hstepA, voffA);
;             G_WAIT_L(8); G_BAR; G_WAIT_L(0); G_MMA(0, 0, At, B0); G_BAR; G_SCHED;
;             G_LDB(B1, 1, 1); G_STAGE(G_SB(1, 0), b3, voffB);
;             G_BAR; G_WAIT_L(0); G_MMA(0, 1, At, B1); G_BAR;
;             G_LDA(At, 1, 1); G_STAGE(G_SA(1, 0), a3, voffA);
	v_mfma_f32_16x16x32_bf16 v[30:33], v[196:199], v[162:165], v[30:33]
	v_mfma_f32_16x16x32_bf16 v[26:29], v[204:207], v[162:165], v[26:29]
	v_mfma_f32_16x16x32_bf16 v[22:25], v[196:199], v[170:173], v[22:25]
	v_mfma_f32_16x16x32_bf16 v[18:21], v[204:207], v[170:173], v[18:21]
	v_mfma_f32_16x16x32_bf16 v[14:17], v[196:199], v[178:181], v[14:17]
	v_mfma_f32_16x16x32_bf16 v[10:13], v[204:207], v[178:181], v[10:13]
	v_mfma_f32_16x16x32_bf16 v[6:9], v[196:199], v[186:189], v[6:9]
	v_mfma_f32_16x16x32_bf16 v[2:5], v[204:207], v[186:189], v[2:5]
	v_mfma_f32_16x16x32_bf16 v[30:33], v[200:203], v[166:169], v[30:33]
	v_mfma_f32_16x16x32_bf16 v[26:29], v[208:211], v[166:169], v[26:29]
	v_mfma_f32_16x16x32_bf16 v[22:25], v[200:203], v[174:177], v[22:25]
	v_mfma_f32_16x16x32_bf16 v[18:21], v[208:211], v[174:177], v[18:21]
	v_mfma_f32_16x16x32_bf16 v[14:17], v[200:203], v[182:185], v[14:17]
	v_mfma_f32_16x16x32_bf16 v[10:13], v[208:211], v[182:185], v[10:13]
	v_mfma_f32_16x16x32_bf16 v[6:9], v[200:203], v[192:195], v[6:9]
	v_mfma_f32_16x16x32_bf16 v[2:5], v[208:211], v[192:195], v[2:5]
	s_add_i32 s10, 0, 0x18000
	v_add_u32_e32 v145, s10, v142
	s_barrier
	ds_read_b128 v[146:149], v145
	ds_read_b128 v[150:153], v145 offset:1024
	ds_read_b128 v[154:157], v145 offset:2048
	ds_read_b128 v[158:161], v145 offset:3072
	s_add_u32 s0, s42, 0x84000
	s_addc_u32 s1, s43, 0
	s_mov_b32 m0, s46
	ds_read_b128 v[162:165], v144 offset:32768
	ds_read_b128 v[166:169], v144 offset:33792
	ds_read_b128 v[170:173], v144 offset:34816
	ds_read_b128 v[174:177], v144 offset:35840
	ds_read_b128 v[178:181], v144 offset:36864
	ds_read_b128 v[182:185], v144 offset:37888
	ds_read_b128 v[186:189], v144 offset:38912
	ds_read_b128 v[192:195], v144 offset:39936
	global_load_lds_dwordx4 v130, s[0:1]
	s_mov_b32 m0, s47
	s_nop 0
	global_load_lds_dwordx4 v134, s[0:1]
	s_waitcnt lgkmcnt(8)
	s_barrier
	s_waitcnt lgkmcnt(0)
	s_waitcnt lgkmcnt(0)
	v_mfma_f32_16x16x32_bf16 v[126:129], v[146:149], v[162:165], v[126:129]
	v_mfma_f32_16x16x32_bf16 v[122:125], v[154:157], v[162:165], v[122:125]
	v_mfma_f32_16x16x32_bf16 v[118:121], v[146:149], v[170:173], v[118:121]
	v_mfma_f32_16x16x32_bf16 v[114:117], v[154:157], v[170:173], v[114:117]
	v_mfma_f32_16x16x32_bf16 v[110:113], v[146:149], v[178:181], v[110:113]
	v_mfma_f32_16x16x32_bf16 v[106:109], v[154:157], v[178:181], v[106:109]
	v_mfma_f32_16x16x32_bf16 v[102:105], v[146:149], v[186:189], v[102:105]
	v_mfma_f32_16x16x32_bf16 v[98:101], v[154:157], v[186:189], v[98:101]
	v_mfma_f32_16x16x32_bf16 v[126:129], v[150:153], v[166:169], v[126:129]
	v_mfma_f32_16x16x32_bf16 v[122:125], v[158:161], v[166:169], v[122:125]
	v_mfma_f32_16x16x32_bf16 v[118:121], v[150:153], v[174:177], v[118:121]
	v_mfma_f32_16x16x32_bf16 v[114:117], v[158:161], v[174:177], v[114:117]
	v_mfma_f32_16x16x32_bf16 v[110:113], v[150:153], v[182:185], v[110:113]
	v_mfma_f32_16x16x32_bf16 v[106:109], v[158:161], v[182:185], v[106:109]
	v_mfma_f32_16x16x32_bf16 v[102:105], v[150:153], v[192:195], v[102:105]
	v_mfma_f32_16x16x32_bf16 v[98:101], v[158:161], v[192:195], v[98:101]
	s_barrier
	s_add_i32 s11, 0, 0x1c000
	s_add_i32 s0, s10, s31
	v_add_u32_e32 v145, s11, v142
	s_add_u32 s98, s40, 0x80
	s_addc_u32 s99, s41, 0
	s_mov_b32 m0, s0
	ds_read_b128 v[196:199], v145
	ds_read_b128 v[200:203], v145 offset:1024
	ds_read_b128 v[204:207], v145 offset:2048
	ds_read_b128 v[208:211], v145 offset:3072
	global_load_lds_dwordx4 v132, s[98:99]
	s_add_i32 m0, s0, 0x2000
	s_nop 0
	global_load_lds_dwordx4 v136, s[98:99]
	s_barrier
; #define G_STAGE(bufoff, gbase, voff) do { _Pragma("unroll") for (int _i = 0; _i < 2; ++_i) \
;         __builtin_amdgcn_global_load_lds((const unsigned*)((const char*)(gbase) + (voff)[_i]), (LAS unsigned*)(lds + (bufoff) + ldsw + _i * 8192), 16, 0, 0); } while (0)
; #define G_WAIT_V(n) asm volatile("s_waitcnt vmcnt(" #n ")" ::: "memory")
; #define G_WAIT_L(n) asm volatile("s_waitcnt lgkmcnt(" #n ")" ::: "memory")
; #define G_BAR __builtin_amdgcn_s_barrier()
; #define G_SCHED __builtin_amdgcn_sched_barrier(0)
; template <int MODE  , class Epi, class Sched>
; __device__ __forceinline__ void gemm_phase(LAS unsigned char* lds, const GemmDesc g, const Sched& S, const Epi& E) {
;     ...
;             G_LDA(At, 1, 1); G_STAGE(G_SA(1, 0), a3, voffA);
;             G_BAR; G_WAIT_L(0); G_MMA(1, 0, At, B0); G_BAR; G_SCHED;
;             G_STAGE(G_SB(1, 1), b3 + hstepB, voffB);
;             G_WAIT_V(6); G_BAR; G_MMA(1, 1, At, B1); G_BAR;
;         }
	s_waitcnt lgkmcnt(0)
	s_waitcnt lgkmcnt(0)
	v_mfma_f32_16x16x32_bf16 v[94:97], v[196:199], v[162:165], v[94:97]
	v_mfma_f32_16x16x32_bf16 v[90:93], v[204:207], v[162:165], v[90:93]
	v_mfma_f32_16x16x32_bf16 v[86:89], v[196:199], v[170:173], v[86:89]
	v_mfma_f32_16x16x32_bf16 v[82:85], v[204:207], v[170:173], v[82:85]
	v_mfma_f32_16x16x32_bf16 v[78:81], v[196:199], v[178:181], v[78:81]
	v_mfma_f32_16x16x32_bf16 v[74:77], v[204:207], v[178:181], v[74:77]
	v_mfma_f32_16x16x32_bf16 v[70:73], v[196:199], v[186:189], v[70:73]
	v_mfma_f32_16x16x32_bf16 v[66:69], v[204:207], v[186:189], v[66:69]
	v_mfma_f32_16x16x32_bf16 v[94:97], v[200:203], v[166:169], v[94:97]
	v_mfma_f32_16x16x32_bf16 v[90:93], v[208:211], v[166:169], v[90:93]
	v_mfma_f32_16x16x32_bf16 v[86:89], v[200:203], v[174:177], v[86:89]
	v_mfma_f32_16x16x32_bf16 v[82:85], v[208:211], v[174:177], v[82:85]
	v_mfma_f32_16x16x32_bf16 v[78:81], v[200:203], v[182:185], v[78:81]
	v_mfma_f32_16x16x32_bf16 v[74:77], v[208:211], v[182:185], v[74:77]
	v_mfma_f32_16x16x32_bf16 v[70:73], v[200:203], v[192:195], v[70:73]
	v_mfma_f32_16x16x32_bf16 v[66:69], v[208:211], v[192:195], v[66:69]
	s_mov_b32 m0, s48
	s_add_u32 s98, s42, 0x80
	s_addc_u32 s99, s43, 0
	s_barrier
	ds_read_b128 v[162:165], v144 offset:49152
	ds_read_b128 v[166:169], v144 offset:50176
	ds_read_b128 v[170:173], v144 offset:51200
	ds_read_b128 v[174:177], v144 offset:52224
	ds_read_b128 v[178:181], v144 offset:53248
	ds_read_b128 v[182:185], v144 offset:54272
	ds_read_b128 v[186:189], v144 offset:55296
	ds_read_b128 v[192:195], v144 offset:56320
	global_load_lds_dwordx4 v130, s[98:99]
	s_mov_b32 m0, s49
	s_nop 0
	global_load_lds_dwordx4 v134, s[98:99]
	s_barrier
	s_waitcnt lgkmcnt(0)
	s_waitcnt lgkmcnt(0)
	v_mfma_f32_16x16x32_bf16 v[62:65], v[146:149], v[162:165], v[62:65]
	v_mfma_f32_16x16x32_bf16 v[58:61], v[154:157], v[162:165], v[58:61]
	v_mfma_f32_16x16x32_bf16 v[54:57], v[146:149], v[170:173], v[54:57]
	v_mfma_f32_16x16x32_bf16 v[50:53], v[154:157], v[170:173], v[50:53]
	v_mfma_f32_16x16x32_bf16 v[46:49], v[146:149], v[178:181], v[46:49]
	v_mfma_f32_16x16x32_bf16 v[42:45], v[154:157], v[178:181], v[42:45]
	v_mfma_f32_16x16x32_bf16 v[38:41], v[146:149], v[186:189], v[38:41]
	v_mfma_f32_16x16x32_bf16 v[34:37], v[154:157], v[186:189], v[34:37]
	v_mfma_f32_16x16x32_bf16 v[62:65], v[150:153], v[166:169], v[62:65]
	v_mfma_f32_16x16x32_bf16 v[58:61], v[158:161], v[166:169], v[58:61]
	v_mfma_f32_16x16x32_bf16 v[54:57], v[150:153], v[174:177], v[54:57]
	v_mfma_f32_16x16x32_bf16 v[50:53], v[158:161], v[174:177], v[50:53]
	v_mfma_f32_16x16x32_bf16 v[46:49], v[150:153], v[182:185], v[46:49]
	v_mfma_f32_16x16x32_bf16 v[42:45], v[158:161], v[182:185], v[42:45]
	v_mfma_f32_16x16x32_bf16 v[38:41], v[150:153], v[192:195], v[38:41]
	v_mfma_f32_16x16x32_bf16 v[34:37], v[158:161], v[192:195], v[34:37]
	s_barrier
	s_add_u32 s0, s40, 0x84080
	s_addc_u32 s1, s41, 0
	s_add_i32 s10, s11, s31
	s_mov_b32 m0, s10
	s_nop 0
	global_load_lds_dwordx4 v132, s[0:1]
	s_add_i32 m0, s10, 0x2000
	s_nop 0
	global_load_lds_dwordx4 v136, s[0:1]
	s_waitcnt vmcnt(6)
	s_barrier
	v_mfma_f32_16x16x32_bf16 v[30:33], v[196:199], v[162:165], v[30:33]
	s_add_i32 s60, s60, 2
	s_add_u32 s15, s15, 0x100
	s_addc_u32 s59, s59, 0
	s_cmp_gt_u32 s60, 13
	s_mov_b64 s[20:21], s[34:35]
	v_mfma_f32_16x16x32_bf16 v[26:29], v[204:207], v[162:165], v[26:29]
	v_mfma_f32_16x16x32_bf16 v[22:25], v[196:199], v[170:173], v[22:25]
	v_mfma_f32_16x16x32_bf16 v[18:21], v[204:207], v[170:173], v[18:21]
	v_mfma_f32_16x16x32_bf16 v[14:17], v[196:199], v[178:181], v[14:17]
	v_mfma_f32_16x16x32_bf16 v[10:13], v[204:207], v[178:181], v[10:13]
	v_mfma_f32_16x16x32_bf16 v[6:9], v[196:199], v[186:189], v[6:9]
	v_mfma_f32_16x16x32_bf16 v[2:5], v[204:207], v[186:189], v[2:5]
	v_mfma_f32_16x16x32_bf16 v[30:33], v[200:203], v[166:169], v[30:33]
	v_mfma_f32_16x16x32_bf16 v[26:29], v[208:211], v[166:169], v[26:29]
	v_mfma_f32_16x16x32_bf16 v[22:25], v[200:203], v[174:177], v[22:25]
	v_mfma_f32_16x16x32_bf16 v[18:21], v[208:211], v[174:177], v[18:21]
	v_mfma_f32_16x16x32_bf16 v[14:17], v[200:203], v[182:185], v[14:17]
	v_mfma_f32_16x16x32_bf16 v[10:13], v[208:211], v[182:185], v[10:13]
	v_mfma_f32_16x16x32_bf16 v[6:9], v[200:203], v[192:195], v[6:9]
	v_mfma_f32_16x16x32_bf16 v[2:5], v[208:211], v[192:195], v[2:5]
	s_cbranch_scc1 .Lkdone_sc
	s_barrier
	s_branch .LBB0_987

; #define G_STAGE(bufoff, gbase, voff) do { _Pragma("unroll") for (int _i = 0; _i < 2; ++_i) \
;         __builtin_amdgcn_global_load_lds((const unsigned*)((const char*)(gbase) + (voff)[_i]), (LAS unsigned*)(lds + (bufoff) + ldsw + _i * 8192), 16, 0, 0); } while (0)
; #define G_WAIT_V(n) asm volatile("s_waitcnt vmcnt(" #n ")" ::: "memory")
; #define G_WAIT_L(n) asm volatile("s_waitcnt lgkmcnt(" #n ")" ::: "memory")
; #define G_BAR __builtin_amdgcn_s_barrier()
; #define G_SCHED __builtin_amdgcn_sched_barrier(0)
; template <int MODE  , class Epi, class Sched>
; __device__ __forceinline__ void gemm_phase(LAS unsigned char* lds, const GemmDesc g, const Sched& S, const Epi& E) {
;     ...
;         for (int t = 0; t < nt; t += 2) {
;             const bool last = (t == nt - 2);
;             const char* a1 = cA + (size_t)(t + 1) * kstep;
;             const char* a2 = last ? nA : cA + (size_t)(t + 2) * kstep; const char* b2 = last ? nB : cB + (size_t)(t + 2) * kstep;
;             const char* a3 = a2 + kstep; const char* b3 = b2 + kstep;
;             G_LDB(B0, 0, 0); G_SCHED; G_LDA(At, 0, 0); G_STAGE(G_SA(1, 1), a1 + hstepA, voffA);
;             G_WAIT_L(8); G_BAR; G_WAIT_L(0); G_MMA(0, 0, At, B0); G_BAR; G_SCHED;
;             G_LDB(B1, 0, 1); G_STAGE(G_SB(0, 0), b2, voffB);
;             G_BAR; G_WAIT_L(0); G_MMA(0, 1, At, B1); G_BAR;
;             G_LDA(At, 0, 1); G_STAGE(G_SA(0, 0), a2, voffA);
;             G_BAR; G_WAIT_L(0); G_MMA(1, 0, At, B0); G_BAR; G_SCHED;
;             G_STAGE(G_SB(0, 1), b2 + hstepB, voffB);
;             G_WAIT_V(6); G_BAR; G_MMA(1, 1, At, B1); G_BAR;
.Lnodb_s1a:
.LBB0_1017:
	ds_read_b128 v[130:133], v163
	ds_read_b128 v[134:137], v163 offset:1024
	ds_read_b128 v[154:157], v163 offset:2048
	ds_read_b128 v[170:173], v163 offset:3072
	s_add_u32 s4, s2, 0x100
	s_addc_u32 s5, s3, 0
	s_cmp_eq_u32 s87, 28
	s_cselect_b32 s53, s47, s5
	s_cselect_b32 s52, s46, s4
	s_cselect_b32 s51, s49, s86
	s_cselect_b32 s50, s48, s85
	s_add_u32 s98, s2, 0x84080
	s_addc_u32 s99, s3, 0
	s_add_i32 m0, s58, 0xc000
	ds_read_b128 v[174:177], v164
	ds_read_b128 v[178:181], v164 offset:1024
	ds_read_b128 v[182:185], v164 offset:2048
	ds_read_b128 v[186:189], v164 offset:3072
	ds_read_b128 v[192:195], v164 offset:4096
	ds_read_b128 v[196:199], v164 offset:5120
	ds_read_b128 v[200:203], v164 offset:6144
	ds_read_b128 v[204:207], v164 offset:7168
	global_load_lds_dwordx4 v138, s[98:99]
	s_add_i32 m0, s58, 0xe000
	s_nop 0
	global_load_lds_dwordx4 v142, s[98:99]
	s_waitcnt lgkmcnt(8)
	s_barrier
	s_waitcnt lgkmcnt(0)
	s_waitcnt lgkmcnt(0)
	v_mfma_f32_16x16x32_bf16 v[126:129], v[130:133], v[174:177], v[126:129]
	v_mfma_f32_16x16x32_bf16 v[122:125], v[154:157], v[174:177], v[122:125]
	v_mfma_f32_16x16x32_bf16 v[110:113], v[130:133], v[182:185], v[110:113]
	v_mfma_f32_16x16x32_bf16 v[106:109], v[154:157], v[182:185], v[106:109]
	v_mfma_f32_16x16x32_bf16 v[94:97], v[130:133], v[192:195], v[94:97]
	v_mfma_f32_16x16x32_bf16 v[90:93], v[154:157], v[192:195], v[90:93]
	v_mfma_f32_16x16x32_bf16 v[78:81], v[130:133], v[200:203], v[78:81]
	v_mfma_f32_16x16x32_bf16 v[74:77], v[154:157], v[200:203], v[74:77]
	v_mfma_f32_16x16x32_bf16 v[126:129], v[134:137], v[178:181], v[126:129]
	v_mfma_f32_16x16x32_bf16 v[122:125], v[170:173], v[178:181], v[122:125]
	v_mfma_f32_16x16x32_bf16 v[110:113], v[134:137], v[186:189], v[110:113]
	v_mfma_f32_16x16x32_bf16 v[106:109], v[170:173], v[186:189], v[106:109]
	v_mfma_f32_16x16x32_bf16 v[94:97], v[134:137], v[196:199], v[94:97]
	v_mfma_f32_16x16x32_bf16 v[90:93], v[170:173], v[196:199], v[90:93]
	v_mfma_f32_16x16x32_bf16 v[78:81], v[134:137], v[204:207], v[78:81]
	v_mfma_f32_16x16x32_bf16 v[74:77], v[170:173], v[204:207], v[74:77]
	s_barrier
	s_add_i32 s0, s66, s57
	s_mov_b32 m0, s0
	ds_read_b128 v[208:211], v165
	ds_read_b128 v[212:215], v165 offset:1024
	ds_read_b128 v[216:219], v165 offset:2048
	ds_read_b128 v[220:223], v165 offset:3072
	global_load_lds_dwordx4 v140, s[50:51]
	s_add_i32 m0, s0, 0x2000
	s_nop 0
	global_load_lds_dwordx4 v144, s[50:51]
	s_barrier
	s_waitcnt lgkmcnt(0)
	s_waitcnt lgkmcnt(0)
	v_mfma_f32_16x16x32_bf16 v[118:121], v[208:211], v[174:177], v[118:121]
	v_mfma_f32_16x16x32_bf16 v[114:117], v[216:219], v[174:177], v[114:117]
	v_mfma_f32_16x16x32_bf16 v[102:105], v[208:211], v[182:185], v[102:105]
	v_mfma_f32_16x16x32_bf16 v[98:101], v[216:219], v[182:185], v[98:101]
	v_mfma_f32_16x16x32_bf16 v[86:89], v[208:211], v[192:195], v[86:89]
	v_mfma_f32_16x16x32_bf16 v[82:85], v[216:219], v[192:195], v[82:85]
	v_mfma_f32_16x16x32_bf16 v[70:73], v[208:211], v[200:203], v[70:73]
	v_mfma_f32_16x16x32_bf16 v[66:69], v[216:219], v[200:203], v[66:69]
	v_mfma_f32_16x16x32_bf16 v[118:121], v[212:215], v[178:181], v[118:121]
	v_mfma_f32_16x16x32_bf16 v[114:117], v[220:223], v[178:181], v[114:117]
	v_mfma_f32_16x16x32_bf16 v[102:105], v[212:215], v[186:189], v[102:105]
	v_mfma_f32_16x16x32_bf16 v[98:101], v[220:223], v[186:189], v[98:101]
	v_mfma_f32_16x16x32_bf16 v[86:89], v[212:215], v[196:199], v[86:89]
	v_mfma_f32_16x16x32_bf16 v[82:85], v[220:223], v[196:199], v[82:85]
	v_mfma_f32_16x16x32_bf16 v[70:73], v[212:215], v[204:207], v[70:73]
	v_mfma_f32_16x16x32_bf16 v[66:69], v[220:223], v[204:207], v[66:69]
	s_mov_b32 m0, s58
	s_barrier
	ds_read_b128 v[174:177], v164 offset:16384
	ds_read_b128 v[178:181], v164 offset:17408
	ds_read_b128 v[182:185], v164 offset:18432
	ds_read_b128 v[186:189], v164 offset:19456
	ds_read_b128 v[192:195], v164 offset:20480
	ds_read_b128 v[196:199], v164 offset:21504
	ds_read_b128 v[200:203], v164 offset:22528
	ds_read_b128 v[204:207], v164 offset:23552
	global_load_lds_dwordx4 v138, s[52:53]
	s_mov_b32 m0, s59
	s_nop 0
	global_load_lds_dwordx4 v142, s[52:53]
	s_barrier
	s_waitcnt lgkmcnt(0)
	s_waitcnt lgkmcnt(0)
	v_mfma_f32_16x16x32_bf16 v[62:65], v[130:133], v[174:177], v[62:65]
	v_mfma_f32_16x16x32_bf16 v[58:61], v[154:157], v[174:177], v[58:61]
	v_mfma_f32_16x16x32_bf16 v[46:49], v[130:133], v[182:185], v[46:49]
	v_mfma_f32_16x16x32_bf16 v[42:45], v[154:157], v[182:185], v[42:45]
	v_mfma_f32_16x16x32_bf16 v[30:33], v[130:133], v[192:195], v[30:33]
	v_mfma_f32_16x16x32_bf16 v[26:29], v[154:157], v[192:195], v[26:29]
	v_mfma_f32_16x16x32_bf16 v[14:17], v[130:133], v[200:203], v[14:17]
	v_mfma_f32_16x16x32_bf16 v[10:13], v[154:157], v[200:203], v[10:13]
	v_mfma_f32_16x16x32_bf16 v[62:65], v[134:137], v[178:181], v[62:65]
	v_mfma_f32_16x16x32_bf16 v[58:61], v[170:173], v[178:181], v[58:61]
	v_mfma_f32_16x16x32_bf16 v[46:49], v[134:137], v[186:189], v[46:49]
	v_mfma_f32_16x16x32_bf16 v[42:45], v[170:173], v[186:189], v[42:45]
	v_mfma_f32_16x16x32_bf16 v[30:33], v[134:137], v[196:199], v[30:33]
	v_mfma_f32_16x16x32_bf16 v[26:29], v[170:173], v[196:199], v[26:29]
	v_mfma_f32_16x16x32_bf16 v[14:17], v[134:137], v[204:207], v[14:17]
	v_mfma_f32_16x16x32_bf16 v[10:13], v[170:173], v[204:207], v[10:13]
	s_barrier
	s_add_u32 s0, s50, 0x84000
	s_addc_u32 s1, s51, 0
	s_add_i32 s2, s67, s57
	s_mov_b32 m0, s2
	s_nop 0
	global_load_lds_dwordx4 v140, s[0:1]
	s_add_i32 m0, s2, 0x2000
	s_nop 0
	global_load_lds_dwordx4 v144, s[0:1]
	s_waitcnt vmcnt(6)
	s_barrier
; #define G_STAGE(bufoff, gbase, voff) do { _Pragma("unroll") for (int _i = 0; _i < 2; ++_i) \
;         __builtin_amdgcn_global_load_lds((const unsigned*)((const char*)(gbase) + (voff)[_i]), (LAS unsigned*)(lds + (bufoff) + ldsw + _i * 8192), 16, 0, 0); } while (0)
; #define G_WAIT_V(n) asm volatile("s_waitcnt vmcnt(" #n ")" ::: "memory")
; #define G_WAIT_L(n) asm volatile("s_waitcnt lgkmcnt(" #n ")" ::: "memory")
; #define G_BAR __builtin_amdgcn_s_barrier()
; #define G_SCHED __builtin_amdgcn_sched_barrier(0)
; template <int MODE  , class Epi, class Sched>
; __device__ __forceinline__ void gemm_phase(LAS unsigned char* lds, const GemmDesc g, const Sched& S, const Epi& E) {
;     ...
;             G_WAIT_V(6); G_BAR; G_MMA(1, 1, At, B1); G_BAR;
;             G_LDB(B0, 1, 0); G_SCHED; G_LDA(At, 1, 0); G_STAGE(G_SA(0, 1), a2 + hstepA, voffA);
;             G_WAIT_L(8); G_BAR; G_WAIT_L(0); G_MMA(0, 0, At, B0); G_BAR; G_SCHED;
;             G_LDB(B1, 1, 1); G_STAGE(G_SB(1, 0), b3, voffB);
;             G_BAR; G_WAIT_L(0); G_MMA(0, 1, At, B1); G_BAR;
;             G_LDA(At, 1, 1); G_STAGE(G_SA(1, 0), a3, voffA);
	v_mfma_f32_16x16x32_bf16 v[54:57], v[208:211], v[174:177], v[54:57]
	v_mfma_f32_16x16x32_bf16 v[50:53], v[216:219], v[174:177], v[50:53]
	v_mfma_f32_16x16x32_bf16 v[38:41], v[208:211], v[182:185], v[38:41]
	v_mfma_f32_16x16x32_bf16 v[34:37], v[216:219], v[182:185], v[34:37]
	v_mfma_f32_16x16x32_bf16 v[22:25], v[208:211], v[192:195], v[22:25]
	v_mfma_f32_16x16x32_bf16 v[18:21], v[216:219], v[192:195], v[18:21]
	v_mfma_f32_16x16x32_bf16 v[6:9], v[208:211], v[200:203], v[6:9]
	v_mfma_f32_16x16x32_bf16 v[2:5], v[216:219], v[200:203], v[2:5]
	v_mfma_f32_16x16x32_bf16 v[54:57], v[212:215], v[178:181], v[54:57]
	v_mfma_f32_16x16x32_bf16 v[50:53], v[220:223], v[178:181], v[50:53]
	v_mfma_f32_16x16x32_bf16 v[38:41], v[212:215], v[186:189], v[38:41]
	v_mfma_f32_16x16x32_bf16 v[34:37], v[220:223], v[186:189], v[34:37]
	v_mfma_f32_16x16x32_bf16 v[22:25], v[212:215], v[196:199], v[22:25]
	v_mfma_f32_16x16x32_bf16 v[18:21], v[220:223], v[196:199], v[18:21]
	v_mfma_f32_16x16x32_bf16 v[6:9], v[212:215], v[204:207], v[6:9]
	v_mfma_f32_16x16x32_bf16 v[2:5], v[220:223], v[204:207], v[2:5]
	s_add_i32 s2, 0, 0x18000
	v_add_u32_e32 v146, s2, v160
	s_barrier
	ds_read_b128 v[130:133], v146
	ds_read_b128 v[134:137], v146 offset:1024
	ds_read_b128 v[154:157], v146 offset:2048
	ds_read_b128 v[170:173], v146 offset:3072
	s_add_u32 s0, s52, 0x84000
	s_addc_u32 s1, s53, 0
	s_mov_b32 m0, s60
	ds_read_b128 v[174:177], v164 offset:32768
	ds_read_b128 v[178:181], v164 offset:33792
	ds_read_b128 v[182:185], v164 offset:34816
	ds_read_b128 v[186:189], v164 offset:35840
	ds_read_b128 v[192:195], v164 offset:36864
	ds_read_b128 v[196:199], v164 offset:37888
	ds_read_b128 v[200:203], v164 offset:38912
	ds_read_b128 v[204:207], v164 offset:39936
	global_load_lds_dwordx4 v138, s[0:1]
	s_mov_b32 m0, s61
	s_nop 0
	global_load_lds_dwordx4 v142, s[0:1]
	s_waitcnt lgkmcnt(8)
	s_barrier
	s_waitcnt lgkmcnt(0)
	s_waitcnt lgkmcnt(0)
	v_mfma_f32_16x16x32_bf16 v[126:129], v[130:133], v[174:177], v[126:129]
	v_mfma_f32_16x16x32_bf16 v[122:125], v[154:157], v[174:177], v[122:125]
	v_mfma_f32_16x16x32_bf16 v[110:113], v[130:133], v[182:185], v[110:113]
	v_mfma_f32_16x16x32_bf16 v[106:109], v[154:157], v[182:185], v[106:109]
	v_mfma_f32_16x16x32_bf16 v[94:97], v[130:133], v[192:195], v[94:97]
	v_mfma_f32_16x16x32_bf16 v[90:93], v[154:157], v[192:195], v[90:93]
	v_mfma_f32_16x16x32_bf16 v[78:81], v[130:133], v[200:203], v[78:81]
	v_mfma_f32_16x16x32_bf16 v[74:77], v[154:157], v[200:203], v[74:77]
	v_mfma_f32_16x16x32_bf16 v[126:129], v[134:137], v[178:181], v[126:129]
	v_mfma_f32_16x16x32_bf16 v[122:125], v[170:173], v[178:181], v[122:125]
	v_mfma_f32_16x16x32_bf16 v[110:113], v[134:137], v[186:189], v[110:113]
	v_mfma_f32_16x16x32_bf16 v[106:109], v[170:173], v[186:189], v[106:109]
	v_mfma_f32_16x16x32_bf16 v[94:97], v[134:137], v[196:199], v[94:97]
	v_mfma_f32_16x16x32_bf16 v[90:93], v[170:173], v[196:199], v[90:93]
	v_mfma_f32_16x16x32_bf16 v[78:81], v[134:137], v[204:207], v[78:81]
	v_mfma_f32_16x16x32_bf16 v[74:77], v[170:173], v[204:207], v[74:77]
	s_barrier
	s_add_i32 s3, 0, 0x1c000
	s_add_i32 s0, s2, s57
	v_add_u32_e32 v146, s3, v160
	s_add_u32 s98, s50, 0x80
	s_addc_u32 s99, s51, 0
	s_mov_b32 m0, s0
	ds_read_b128 v[208:211], v146
	ds_read_b128 v[212:215], v146 offset:1024
	ds_read_b128 v[216:219], v146 offset:2048
	ds_read_b128 v[220:223], v146 offset:3072
	global_load_lds_dwordx4 v140, s[98:99]
	s_add_i32 m0, s0, 0x2000
	s_nop 0
	global_load_lds_dwordx4 v144, s[98:99]
	s_barrier
; #define G_STAGE(bufoff, gbase, voff) do { _Pragma("unroll") for (int _i = 0; _i < 2; ++_i) \
;         __builtin_amdgcn_global_load_lds((const unsigned*)((const char*)(gbase) + (voff)[_i]), (LAS unsigned*)(lds + (bufoff) + ldsw + _i * 8192), 16, 0, 0); } while (0)
; #define G_WAIT_V(n) asm volatile("s_waitcnt vmcnt(" #n ")" ::: "memory")
; #define G_WAIT_L(n) asm volatile("s_waitcnt lgkmcnt(" #n ")" ::: "memory")
; #define G_BAR __builtin_amdgcn_s_barrier()
; #define G_SCHED __builtin_amdgcn_sched_barrier(0)
; template <int MODE  , class Epi, class Sched>
; __device__ __forceinline__ void gemm_phase(LAS unsigned char* lds, const GemmDesc g, const Sched& S, const Epi& E) {
;     ...
;             G_LDA(At, 1, 1); G_STAGE(G_SA(1, 0), a3, voffA);
;             G_BAR; G_WAIT_L(0); G_MMA(1, 0, At, B0); G_BAR; G_SCHED;
;             G_STAGE(G_SB(1, 1), b3 + hstepB, voffB);
;             G_WAIT_V(6); G_BAR; G_MMA(1, 1, At, B1); G_BAR;
;         }
	s_waitcnt lgkmcnt(0)
	s_waitcnt lgkmcnt(0)
	v_mfma_f32_16x16x32_bf16 v[118:121], v[208:211], v[174:177], v[118:121]
	v_mfma_f32_16x16x32_bf16 v[114:117], v[216:219], v[174:177], v[114:117]
	v_mfma_f32_16x16x32_bf16 v[102:105], v[208:211], v[182:185], v[102:105]
	v_mfma_f32_16x16x32_bf16 v[98:101], v[216:219], v[182:185], v[98:101]
	v_mfma_f32_16x16x32_bf16 v[86:89], v[208:211], v[192:195], v[86:89]
	v_mfma_f32_16x16x32_bf16 v[82:85], v[216:219], v[192:195], v[82:85]
	v_mfma_f32_16x16x32_bf16 v[70:73], v[208:211], v[200:203], v[70:73]
	v_mfma_f32_16x16x32_bf16 v[66:69], v[216:219], v[200:203], v[66:69]
	v_mfma_f32_16x16x32_bf16 v[118:121], v[212:215], v[178:181], v[118:121]
	v_mfma_f32_16x16x32_bf16 v[114:117], v[220:223], v[178:181], v[114:117]
	v_mfma_f32_16x16x32_bf16 v[102:105], v[212:215], v[186:189], v[102:105]
	v_mfma_f32_16x16x32_bf16 v[98:101], v[220:223], v[186:189], v[98:101]
	v_mfma_f32_16x16x32_bf16 v[86:89], v[212:215], v[196:199], v[86:89]
	v_mfma_f32_16x16x32_bf16 v[82:85], v[220:223], v[196:199], v[82:85]
	v_mfma_f32_16x16x32_bf16 v[70:73], v[212:215], v[204:207], v[70:73]
	v_mfma_f32_16x16x32_bf16 v[66:69], v[220:223], v[204:207], v[66:69]
	s_mov_b32 m0, s64
	s_add_u32 s98, s52, 0x80
	s_addc_u32 s99, s53, 0
	s_barrier
	ds_read_b128 v[174:177], v164 offset:49152
	ds_read_b128 v[178:181], v164 offset:50176
	ds_read_b128 v[182:185], v164 offset:51200
	ds_read_b128 v[186:189], v164 offset:52224
	ds_read_b128 v[192:195], v164 offset:53248
	ds_read_b128 v[196:199], v164 offset:54272
	ds_read_b128 v[200:203], v164 offset:55296
	ds_read_b128 v[204:207], v164 offset:56320
	global_load_lds_dwordx4 v138, s[98:99]
	s_mov_b32 m0, s65
	s_nop 0
	global_load_lds_dwordx4 v142, s[98:99]
	s_barrier
	s_waitcnt lgkmcnt(0)
	s_waitcnt lgkmcnt(0)
	v_mfma_f32_16x16x32_bf16 v[62:65], v[130:133], v[174:177], v[62:65]
	v_mfma_f32_16x16x32_bf16 v[58:61], v[154:157], v[174:177], v[58:61]
	v_mfma_f32_16x16x32_bf16 v[46:49], v[130:133], v[182:185], v[46:49]
	v_mfma_f32_16x16x32_bf16 v[42:45], v[154:157], v[182:185], v[42:45]
	v_mfma_f32_16x16x32_bf16 v[30:33], v[130:133], v[192:195], v[30:33]
	v_mfma_f32_16x16x32_bf16 v[26:29], v[154:157], v[192:195], v[26:29]
	v_mfma_f32_16x16x32_bf16 v[14:17], v[130:133], v[200:203], v[14:17]
	v_mfma_f32_16x16x32_bf16 v[10:13], v[154:157], v[200:203], v[10:13]
	v_mfma_f32_16x16x32_bf16 v[62:65], v[134:137], v[178:181], v[62:65]
	v_mfma_f32_16x16x32_bf16 v[58:61], v[170:173], v[178:181], v[58:61]
	v_mfma_f32_16x16x32_bf16 v[46:49], v[134:137], v[186:189], v[46:49]
	v_mfma_f32_16x16x32_bf16 v[42:45], v[170:173], v[186:189], v[42:45]
	v_mfma_f32_16x16x32_bf16 v[30:33], v[134:137], v[196:199], v[30:33]
	v_mfma_f32_16x16x32_bf16 v[26:29], v[170:173], v[196:199], v[26:29]
	v_mfma_f32_16x16x32_bf16 v[14:17], v[134:137], v[204:207], v[14:17]
	v_mfma_f32_16x16x32_bf16 v[10:13], v[170:173], v[204:207], v[10:13]
	s_barrier
	s_add_u32 s0, s50, 0x84080
	s_addc_u32 s1, s51, 0
	s_add_i32 s2, s3, s57
	s_mov_b32 m0, s2
	s_nop 0
	global_load_lds_dwordx4 v140, s[0:1]
	s_add_i32 m0, s2, 0x2000
	s_nop 0
	global_load_lds_dwordx4 v144, s[0:1]
	s_waitcnt vmcnt(6)
	s_barrier
	v_mfma_f32_16x16x32_bf16 v[54:57], v[208:211], v[174:177], v[54:57]
	s_add_i32 s87, s87, 2
	s_add_u32 s85, s85, 0x100
	s_addc_u32 s86, s86, 0
	s_cmp_gt_u32 s87, 29
	s_mov_b64 s[2:3], s[4:5]
	v_mfma_f32_16x16x32_bf16 v[50:53], v[216:219], v[174:177], v[50:53]
	v_mfma_f32_16x16x32_bf16 v[38:41], v[208:211], v[182:185], v[38:41]
	v_mfma_f32_16x16x32_bf16 v[34:37], v[216:219], v[182:185], v[34:37]
	v_mfma_f32_16x16x32_bf16 v[22:25], v[208:211], v[192:195], v[22:25]
	v_mfma_f32_16x16x32_bf16 v[18:21], v[216:219], v[192:195], v[18:21]
	v_mfma_f32_16x16x32_bf16 v[6:9], v[208:211], v[200:203], v[6:9]
	v_mfma_f32_16x16x32_bf16 v[2:5], v[216:219], v[200:203], v[2:5]
	v_mfma_f32_16x16x32_bf16 v[54:57], v[212:215], v[178:181], v[54:57]
	v_mfma_f32_16x16x32_bf16 v[50:53], v[220:223], v[178:181], v[50:53]
	v_mfma_f32_16x16x32_bf16 v[38:41], v[212:215], v[186:189], v[38:41]
	v_mfma_f32_16x16x32_bf16 v[34:37], v[220:223], v[186:189], v[34:37]
	v_mfma_f32_16x16x32_bf16 v[22:25], v[212:215], v[196:199], v[22:25]
	v_mfma_f32_16x16x32_bf16 v[18:21], v[220:223], v[196:199], v[18:21]
	v_mfma_f32_16x16x32_bf16 v[6:9], v[212:215], v[204:207], v[6:9]
	v_mfma_f32_16x16x32_bf16 v[2:5], v[220:223], v[204:207], v[2:5]
	s_cbranch_scc1 .Lkdone_s1a
	s_barrier
	s_branch .LBB0_1017
